# lever 4: one static s_setprio 1 for waves 4-7 in the 7 GEMM mainloops, per-phase priority flips deleted
# baseline (speedup 1.0000x reference)
; #define PG8_STAGE(bufoff, gbase, voff) do { _Pragma("unroll") for (int _i = 0; _i < 2; ++_i) { unsigned _vo = (voff)[_i]; asm volatile("" : "+v"(_vo));   \
;         __builtin_amdgcn_global_load_lds((const unsigned*)((const char*)(gbase) + _vo), (LAS unsigned*)(lds + (bufoff) + ldsw + _i * 8192), 16, 0, 0); } } while (0)
; #define PG8_LDA(dst, b, h) do { _Pragma("unroll") for (int m = 0; m < 4; ++m) _Pragma("unroll") for (int k = 0; k < 2; ++k) dst[m][k] = *(const LAS bf16x8*)(lds + PG8_SA(b, h) + aoff + m * 2048 + k * 1024); } while (0)
; #define PG8_LDB(dst, b, h) do { _Pragma("unroll") for (int n = 0; n < 2; ++n) _Pragma("unroll") for (int k = 0; k < 2; ++k) dst[n][k] = *(const LAS bf16x8*)(lds + PG8_SB(b, h) + boff + n * 2048 + k * 1024); } while (0)
; #define PG8_WAIT_V(n) asm volatile("s_waitcnt vmcnt(" #n ")" ::: "memory")
; template <bool F8 = false>
; __device__ __forceinline__ void gemm_phase(LAS unsigned char* lds, const int K, const Sched& S, const Epi& E, const int wave_s) {
;     ...
;         for (int t = 0; t < nt; t += 2) {
;             const bool last = (t == nt - 2);
;             const char* a1 = cA + (size_t)(t + 1) * kstep;
;             const char* a2 = last ? nA : cA + (size_t)(t + 2) * kstep; const char* b2 = last ? nB : cB + (size_t)(t + 2) * kstep;
;             const char* a3 = a2 + kstep; const char* b3 = b2 + kstep;
;             PG8_LDB(B0, 0, 0); PG8_LDB(B1, 0, 1); PG8_SCHED; PG8_LDA(At, 0, 0); PG8_STAGE(PG8_SA(1, 1), a1 + hstepA, voffA);
;             PG8_WAIT_V(8); PG8_WAIT_L(0); PG8_BAR; PG8_MMA(0, 0, At, B0); PG8_MMA(0, 1, At, B1); PG8_BAR; PG8_SCHED;
;             PG8_LDA(At, 0, 1); PG8_STAGE(PG8_SB(0, 0), b2, voffB); PG8_STAGE(PG8_SB(0, 1), b2 + hstepB, voffB); PG8_STAGE(PG8_SA(0, 0), a2, voffA);
;             PG8_WAIT_V(8); PG8_WAIT_L(0); PG8_BAR; PG8_MMA(1, 0, At, B0); PG8_MMA(1, 1, At, B1); PG8_BAR; PG8_SCHED;
;             PG8_LDB(B0, 1, 0); PG8_LDB(B1, 1, 1); PG8_SCHED; PG8_LDA(At, 1, 0); PG8_STAGE(PG8_SA(0, 1), a2 + hstepA, voffA);
;             PG8_WAIT_V(8); PG8_WAIT_L(0); PG8_BAR; PG8_MMA(0, 0, At, B0); PG8_MMA(0, 1, At, B1); PG8_BAR; PG8_SCHED;
;             PG8_LDA(At, 1, 1); PG8_STAGE(PG8_SB(1, 0), b3, voffB); PG8_STAGE(PG8_SB(1, 1), b3 + hstepB, voffB); PG8_STAGE(PG8_SA(1, 0), a3, voffA);
;             PG8_WAIT_V(8); PG8_WAIT_L(0); PG8_BAR; PG8_MMA(1, 0, At, B0); PG8_MMA(1, 1, At, B1); PG8_BAR; PG8_SCHED;
.LBB0_421:
	s_cmp_eq_u32 s78, 1
	s_cbranch_scc0 .Lmy_prio0
	s_setprio 1
.Lmy_prio0:
	ds_read_b128 v[132:135], v143
	ds_read_b128 v[146:149], v143 offset:1024
	ds_read_b128 v[150:153], v143 offset:2048
	ds_read_b128 v[154:157], v143 offset:3072
	ds_read_b128 v[158:161], v144
	ds_read_b128 v[162:165], v144 offset:1024
	ds_read_b128 v[166:169], v144 offset:2048
	ds_read_b128 v[170:173], v144 offset:3072
	s_add_u32 s44, s8, 0xfffc0080
	s_addc_u32 s45, s9, -1
	s_cmp_eq_u32 s89, 12
	s_cselect_b32 s45, s7, s45
	s_cselect_b32 s44, s37, s44
	s_cselect_b32 s47, s49, s88
	s_cselect_b32 s46, s62, s63
	v_mov_b32_e32 v128, v138
	ds_read_b128 v[174:177], v145
	ds_read_b128 v[178:181], v145 offset:1024
	ds_read_b128 v[182:185], v145 offset:2048
	ds_read_b128 v[186:189], v145 offset:3072
	ds_read_b128 v[190:193], v145 offset:4096
	ds_read_b128 v[194:197], v145 offset:5120
	ds_read_b128 v[198:201], v145 offset:6144
	ds_read_b128 v[202:205], v145 offset:7168
	s_add_i32 m0, s50, 0xc000
	s_nop 0
	global_load_lds_dwordx4 v128, s[8:9]
	v_mov_b32_e32 v128, v140
	s_add_i32 m0, s50, 0xe000
	s_nop 0
	global_load_lds_dwordx4 v128, s[8:9]
	s_waitcnt vmcnt(8)
	s_waitcnt lgkmcnt(0)
	s_barrier
	s_waitcnt lgkmcnt(0)
	v_mfma_i32_16x16x64_i8 v[124:127], v[132:135], v[174:177], v[124:127]
	v_mfma_i32_16x16x64_i8 v[120:123], v[150:153], v[174:177], v[120:123]
	v_mfma_i32_16x16x64_i8 v[108:111], v[132:135], v[182:185], v[108:111]
	v_mfma_i32_16x16x64_i8 v[104:107], v[150:153], v[182:185], v[104:107]
	v_mfma_i32_16x16x64_i8 v[92:95], v[132:135], v[190:193], v[92:95]
	v_mfma_i32_16x16x64_i8 v[88:91], v[150:153], v[190:193], v[88:91]
	v_mfma_i32_16x16x64_i8 v[76:79], v[132:135], v[198:201], v[76:79]
	v_mfma_i32_16x16x64_i8 v[72:75], v[150:153], v[198:201], v[72:75]
	v_mfma_i32_16x16x64_i8 v[124:127], v[146:149], v[178:181], v[124:127]
	v_mfma_i32_16x16x64_i8 v[120:123], v[154:157], v[178:181], v[120:123]
	v_mfma_i32_16x16x64_i8 v[108:111], v[146:149], v[186:189], v[108:111]
	v_mfma_i32_16x16x64_i8 v[104:107], v[154:157], v[186:189], v[104:107]
	v_mfma_i32_16x16x64_i8 v[92:95], v[146:149], v[194:197], v[92:95]
	v_mfma_i32_16x16x64_i8 v[88:91], v[154:157], v[194:197], v[88:91]
	v_mfma_i32_16x16x64_i8 v[76:79], v[146:149], v[202:205], v[76:79]
	v_mfma_i32_16x16x64_i8 v[72:75], v[154:157], v[202:205], v[72:75]
	v_mfma_i32_16x16x64_i8 v[116:119], v[158:161], v[174:177], v[116:119]
	v_mfma_i32_16x16x64_i8 v[112:115], v[166:169], v[174:177], v[112:115]
	v_mfma_i32_16x16x64_i8 v[100:103], v[158:161], v[182:185], v[100:103]
	v_mfma_i32_16x16x64_i8 v[96:99], v[166:169], v[182:185], v[96:99]
	v_mfma_i32_16x16x64_i8 v[84:87], v[158:161], v[190:193], v[84:87]
	v_mfma_i32_16x16x64_i8 v[80:83], v[166:169], v[190:193], v[80:83]
	v_mfma_i32_16x16x64_i8 v[68:71], v[158:161], v[198:201], v[68:71]
	v_mfma_i32_16x16x64_i8 v[64:67], v[166:169], v[198:201], v[64:67]
	v_mfma_i32_16x16x64_i8 v[116:119], v[162:165], v[178:181], v[116:119]
	v_mfma_i32_16x16x64_i8 v[112:115], v[170:173], v[178:181], v[112:115]
	v_mfma_i32_16x16x64_i8 v[100:103], v[162:165], v[186:189], v[100:103]
	v_mfma_i32_16x16x64_i8 v[96:99], v[170:173], v[186:189], v[96:99]
	v_mfma_i32_16x16x64_i8 v[84:87], v[162:165], v[194:197], v[84:87]
	v_mfma_i32_16x16x64_i8 v[80:83], v[170:173], v[194:197], v[80:83]
	v_mfma_i32_16x16x64_i8 v[68:71], v[162:165], v[202:205], v[68:71]
	v_mfma_i32_16x16x64_i8 v[64:67], v[170:173], v[202:205], v[64:67]
	s_barrier
	v_mov_b32_e32 v128, v139
	s_add_i32 s91, s83, s73
	ds_read_b128 v[174:177], v145 offset:16384
	ds_read_b128 v[178:181], v145 offset:17408
	ds_read_b128 v[182:185], v145 offset:18432
	ds_read_b128 v[186:189], v145 offset:19456
	ds_read_b128 v[190:193], v145 offset:20480
	ds_read_b128 v[194:197], v145 offset:21504
	ds_read_b128 v[198:201], v145 offset:22528
	ds_read_b128 v[202:205], v145 offset:23552
	s_mov_b32 m0, s91
	s_nop 0
	global_load_lds_dwordx4 v128, s[46:47]
	v_mov_b32_e32 v128, v141
	s_add_i32 m0, s91, 0x2000
	s_add_u32 s92, s46, 0x40000
	global_load_lds_dwordx4 v128, s[46:47]
	s_addc_u32 s93, s47, 0
	v_mov_b32_e32 v128, v139
	s_add_i32 s91, s84, s73
	s_mov_b32 m0, s91
	s_nop 0
	global_load_lds_dwordx4 v128, s[92:93]
	v_mov_b32_e32 v128, v141
	s_add_i32 m0, s91, 0x2000
	s_nop 0
	global_load_lds_dwordx4 v128, s[92:93]
	v_mov_b32_e32 v128, v138
	s_mov_b32 m0, s50
	s_nop 0
	global_load_lds_dwordx4 v128, s[44:45]
	v_mov_b32_e32 v128, v140
	s_mov_b32 m0, s51
	s_nop 0
	global_load_lds_dwordx4 v128, s[44:45]
	s_waitcnt vmcnt(8)
	s_waitcnt lgkmcnt(0)
	s_barrier
	s_waitcnt lgkmcnt(0)
	v_mfma_i32_16x16x64_i8 v[60:63], v[132:135], v[174:177], v[60:63]
	v_mfma_i32_16x16x64_i8 v[56:59], v[150:153], v[174:177], v[56:59]
	v_mfma_i32_16x16x64_i8 v[44:47], v[132:135], v[182:185], v[44:47]
	v_mfma_i32_16x16x64_i8 v[40:43], v[150:153], v[182:185], v[40:43]
	v_mfma_i32_16x16x64_i8 v[28:31], v[132:135], v[190:193], v[28:31]
	v_mfma_i32_16x16x64_i8 v[24:27], v[150:153], v[190:193], v[24:27]
	v_mfma_i32_16x16x64_i8 v[12:15], v[132:135], v[198:201], v[12:15]
	v_mfma_i32_16x16x64_i8 v[8:11], v[150:153], v[198:201], v[8:11]
	v_mfma_i32_16x16x64_i8 v[60:63], v[146:149], v[178:181], v[60:63]
	v_mfma_i32_16x16x64_i8 v[56:59], v[154:157], v[178:181], v[56:59]
	v_mfma_i32_16x16x64_i8 v[44:47], v[146:149], v[186:189], v[44:47]
	v_mfma_i32_16x16x64_i8 v[40:43], v[154:157], v[186:189], v[40:43]
	v_mfma_i32_16x16x64_i8 v[28:31], v[146:149], v[194:197], v[28:31]
	v_mfma_i32_16x16x64_i8 v[24:27], v[154:157], v[194:197], v[24:27]
	v_mfma_i32_16x16x64_i8 v[12:15], v[146:149], v[202:205], v[12:15]
	v_mfma_i32_16x16x64_i8 v[8:11], v[154:157], v[202:205], v[8:11]
	v_mfma_i32_16x16x64_i8 v[52:55], v[158:161], v[174:177], v[52:55]
	v_mfma_i32_16x16x64_i8 v[48:51], v[166:169], v[174:177], v[48:51]
	v_mfma_i32_16x16x64_i8 v[36:39], v[158:161], v[182:185], v[36:39]
	v_mfma_i32_16x16x64_i8 v[32:35], v[166:169], v[182:185], v[32:35]
	v_mfma_i32_16x16x64_i8 v[20:23], v[158:161], v[190:193], v[20:23]
	v_mfma_i32_16x16x64_i8 v[16:19], v[166:169], v[190:193], v[16:19]
	v_mfma_i32_16x16x64_i8 v[4:7], v[158:161], v[198:201], v[4:7]
	v_mfma_i32_16x16x64_i8 v[0:3], v[166:169], v[198:201], v[0:3]
	v_mfma_i32_16x16x64_i8 v[52:55], v[162:165], v[178:181], v[52:55]
	v_mfma_i32_16x16x64_i8 v[48:51], v[170:173], v[178:181], v[48:51]
	v_mfma_i32_16x16x64_i8 v[36:39], v[162:165], v[186:189], v[36:39]
	v_mfma_i32_16x16x64_i8 v[32:35], v[170:173], v[186:189], v[32:35]
	v_mfma_i32_16x16x64_i8 v[20:23], v[162:165], v[194:197], v[20:23]
	v_mfma_i32_16x16x64_i8 v[16:19], v[170:173], v[194:197], v[16:19]
	v_mfma_i32_16x16x64_i8 v[4:7], v[162:165], v[202:205], v[4:7]
	v_mfma_i32_16x16x64_i8 v[0:3], v[170:173], v[202:205], v[0:3]
	s_barrier
; #define PG8_STAGE(bufoff, gbase, voff) do { _Pragma("unroll") for (int _i = 0; _i < 2; ++_i) { unsigned _vo = (voff)[_i]; asm volatile("" : "+v"(_vo));   \
;         __builtin_amdgcn_global_load_lds((const unsigned*)((const char*)(gbase) + _vo), (LAS unsigned*)(lds + (bufoff) + ldsw + _i * 8192), 16, 0, 0); } } while (0)
; #define PG8_LDA(dst, b, h) do { _Pragma("unroll") for (int m = 0; m < 4; ++m) _Pragma("unroll") for (int k = 0; k < 2; ++k) dst[m][k] = *(const LAS bf16x8*)(lds + PG8_SA(b, h) + aoff + m * 2048 + k * 1024); } while (0)
; #define PG8_LDB(dst, b, h) do { _Pragma("unroll") for (int n = 0; n < 2; ++n) _Pragma("unroll") for (int k = 0; k < 2; ++k) dst[n][k] = *(const LAS bf16x8*)(lds + PG8_SB(b, h) + boff + n * 2048 + k * 1024); } while (0)
; #define PG8_WAIT_V(n) asm volatile("s_waitcnt vmcnt(" #n ")" ::: "memory")
; #define PG8_WAIT_L(n) asm volatile("s_waitcnt lgkmcnt(" #n ")" ::: "memory")
; #define PG8_BAR __builtin_amdgcn_s_barrier()
; #define PG8_SCHED __builtin_amdgcn_sched_barrier(0)
; template <bool F8 = false>
; __device__ __forceinline__ void gemm_phase(LAS unsigned char* lds, const int K, const Sched& S, const Epi& E, const int wave_s) {
;     ...
;             PG8_LDB(B0, 1, 0); PG8_LDB(B1, 1, 1); PG8_SCHED; PG8_LDA(At, 1, 0); PG8_STAGE(PG8_SA(0, 1), a2 + hstepA, voffA);
;             PG8_WAIT_V(8); PG8_WAIT_L(0); PG8_BAR; PG8_MMA(0, 0, At, B0); PG8_MMA(0, 1, At, B1); PG8_BAR; PG8_SCHED;
;             PG8_LDA(At, 1, 1); PG8_STAGE(PG8_SB(1, 0), b3, voffB); PG8_STAGE(PG8_SB(1, 1), b3 + hstepB, voffB); PG8_STAGE(PG8_SA(1, 0), a3, voffA);
;             PG8_WAIT_V(8); PG8_WAIT_L(0); PG8_BAR; PG8_MMA(1, 0, At, B0); PG8_MMA(1, 1, At, B1); PG8_BAR; PG8_SCHED;
	s_add_i32 s91, 0, 0x18000
	v_add_u32_e32 v128, s91, v142
	s_add_i32 s94, 0, 0x1c000
	ds_read_b128 v[132:135], v128
	ds_read_b128 v[146:149], v128 offset:1024
	ds_read_b128 v[150:153], v128 offset:2048
	ds_read_b128 v[154:157], v128 offset:3072
	v_add_u32_e32 v128, s94, v142
	ds_read_b128 v[158:161], v128
	ds_read_b128 v[162:165], v128 offset:1024
	ds_read_b128 v[166:169], v128 offset:2048
	ds_read_b128 v[170:173], v128 offset:3072
	s_add_u32 s92, s44, 0x40000
	v_mov_b32_e32 v128, v138
	s_mov_b32 m0, s61
	ds_read_b128 v[174:177], v145 offset:32768
	ds_read_b128 v[178:181], v145 offset:33792
	ds_read_b128 v[182:185], v145 offset:34816
	ds_read_b128 v[186:189], v145 offset:35840
	ds_read_b128 v[190:193], v145 offset:36864
	ds_read_b128 v[194:197], v145 offset:37888
	ds_read_b128 v[198:201], v145 offset:38912
	ds_read_b128 v[202:205], v145 offset:39936
	s_addc_u32 s93, s45, 0
	s_nop 0
	global_load_lds_dwordx4 v128, s[92:93]
	v_mov_b32_e32 v128, v140
	s_mov_b32 m0, s69
	s_nop 0
	global_load_lds_dwordx4 v128, s[92:93]
	s_waitcnt vmcnt(8)
	s_waitcnt lgkmcnt(0)
	s_barrier
	s_waitcnt lgkmcnt(0)
	v_mfma_i32_16x16x64_i8 v[124:127], v[132:135], v[174:177], v[124:127]
	v_mfma_i32_16x16x64_i8 v[120:123], v[150:153], v[174:177], v[120:123]
	v_mfma_i32_16x16x64_i8 v[108:111], v[132:135], v[182:185], v[108:111]
	v_mfma_i32_16x16x64_i8 v[104:107], v[150:153], v[182:185], v[104:107]
	v_mfma_i32_16x16x64_i8 v[92:95], v[132:135], v[190:193], v[92:95]
	v_mfma_i32_16x16x64_i8 v[88:91], v[150:153], v[190:193], v[88:91]
	v_mfma_i32_16x16x64_i8 v[76:79], v[132:135], v[198:201], v[76:79]
	v_mfma_i32_16x16x64_i8 v[72:75], v[150:153], v[198:201], v[72:75]
	v_mfma_i32_16x16x64_i8 v[124:127], v[146:149], v[178:181], v[124:127]
	v_mfma_i32_16x16x64_i8 v[120:123], v[154:157], v[178:181], v[120:123]
	v_mfma_i32_16x16x64_i8 v[108:111], v[146:149], v[186:189], v[108:111]
	v_mfma_i32_16x16x64_i8 v[104:107], v[154:157], v[186:189], v[104:107]
	v_mfma_i32_16x16x64_i8 v[92:95], v[146:149], v[194:197], v[92:95]
	v_mfma_i32_16x16x64_i8 v[88:91], v[154:157], v[194:197], v[88:91]
	v_mfma_i32_16x16x64_i8 v[76:79], v[146:149], v[202:205], v[76:79]
	v_mfma_i32_16x16x64_i8 v[72:75], v[154:157], v[202:205], v[72:75]
	v_mfma_i32_16x16x64_i8 v[116:119], v[158:161], v[174:177], v[116:119]
	v_mfma_i32_16x16x64_i8 v[112:115], v[166:169], v[174:177], v[112:115]
	v_mfma_i32_16x16x64_i8 v[100:103], v[158:161], v[182:185], v[100:103]
	v_mfma_i32_16x16x64_i8 v[96:99], v[166:169], v[182:185], v[96:99]
	v_mfma_i32_16x16x64_i8 v[84:87], v[158:161], v[190:193], v[84:87]
	v_mfma_i32_16x16x64_i8 v[80:83], v[166:169], v[190:193], v[80:83]
	v_mfma_i32_16x16x64_i8 v[68:71], v[158:161], v[198:201], v[68:71]
	v_mfma_i32_16x16x64_i8 v[64:67], v[166:169], v[198:201], v[64:67]
	v_mfma_i32_16x16x64_i8 v[116:119], v[162:165], v[178:181], v[116:119]
	v_mfma_i32_16x16x64_i8 v[112:115], v[170:173], v[178:181], v[112:115]
	v_mfma_i32_16x16x64_i8 v[100:103], v[162:165], v[186:189], v[100:103]
	v_mfma_i32_16x16x64_i8 v[96:99], v[170:173], v[186:189], v[96:99]
	v_mfma_i32_16x16x64_i8 v[84:87], v[162:165], v[194:197], v[84:87]
	v_mfma_i32_16x16x64_i8 v[80:83], v[170:173], v[194:197], v[80:83]
	v_mfma_i32_16x16x64_i8 v[68:71], v[162:165], v[202:205], v[68:71]
	v_mfma_i32_16x16x64_i8 v[64:67], v[170:173], v[202:205], v[64:67]
	s_barrier
; #define PG8_STAGE(bufoff, gbase, voff) do { _Pragma("unroll") for (int _i = 0; _i < 2; ++_i) { unsigned _vo = (voff)[_i]; asm volatile("" : "+v"(_vo));   \
;         __builtin_amdgcn_global_load_lds((const unsigned*)((const char*)(gbase) + _vo), (LAS unsigned*)(lds + (bufoff) + ldsw + _i * 8192), 16, 0, 0); } } while (0)
; #define PG8_LDA(dst, b, h) do { _Pragma("unroll") for (int m = 0; m < 4; ++m) _Pragma("unroll") for (int k = 0; k < 2; ++k) dst[m][k] = *(const LAS bf16x8*)(lds + PG8_SA(b, h) + aoff + m * 2048 + k * 1024); } while (0)
; #define PG8_LDB(dst, b, h) do { _Pragma("unroll") for (int n = 0; n < 2; ++n) _Pragma("unroll") for (int k = 0; k < 2; ++k) dst[n][k] = *(const LAS bf16x8*)(lds + PG8_SB(b, h) + boff + n * 2048 + k * 1024); } while (0)
; #define PG8_WAIT_V(n) asm volatile("s_waitcnt vmcnt(" #n ")" ::: "memory")
; #define PG8_WAIT_L(n) asm volatile("s_waitcnt lgkmcnt(" #n ")" ::: "memory")
; #define PG8_BAR __builtin_amdgcn_s_barrier()
; #define PG8_SCHED __builtin_amdgcn_sched_barrier(0)
; template <bool F8 = false>
; __device__ __forceinline__ void gemm_phase(LAS unsigned char* lds, const int K, const Sched& S, const Epi& E, const int wave_s) {
;     ...
;             PG8_LDB(B0, 1, 0); PG8_LDB(B1, 1, 1); PG8_SCHED; PG8_LDA(At, 1, 0); PG8_STAGE(PG8_SA(0, 1), a2 + hstepA, voffA);
;             PG8_WAIT_V(8); PG8_WAIT_L(0); PG8_BAR; PG8_MMA(0, 0, At, B0); PG8_MMA(0, 1, At, B1); PG8_BAR; PG8_SCHED;
;             PG8_LDA(At, 1, 1); PG8_STAGE(PG8_SB(1, 0), b3, voffB); PG8_STAGE(PG8_SB(1, 1), b3 + hstepB, voffB); PG8_STAGE(PG8_SA(1, 0), a3, voffA);
;             PG8_WAIT_V(8); PG8_WAIT_L(0); PG8_BAR; PG8_MMA(1, 0, At, B0); PG8_MMA(1, 1, At, B1); PG8_BAR; PG8_SCHED;
;         }
	v_mov_b32_e32 v128, v139
	ds_read_b128 v[174:177], v145 offset:49152
	ds_read_b128 v[178:181], v145 offset:50176
	ds_read_b128 v[182:185], v145 offset:51200
	ds_read_b128 v[186:189], v145 offset:52224
	ds_read_b128 v[190:193], v145 offset:53248
	ds_read_b128 v[194:197], v145 offset:54272
	ds_read_b128 v[198:201], v145 offset:55296
	ds_read_b128 v[202:205], v145 offset:56320
	s_add_i32 s91, s91, s73
	v_lshl_add_u64 v[136:137], s[46:47], 0, v[128:129]
	v_lshl_add_u64 v[136:137], v[136:137], 0, s[12:13]
	s_mov_b32 m0, s91
	v_mov_b32_e32 v128, v141
	global_load_lds_dwordx4 v[136:137], off
	s_add_i32 m0, s91, 0x2000
	s_nop 0
	v_lshl_add_u64 v[136:137], s[46:47], 0, v[128:129]
	s_add_u32 s46, s46, 0x40080
	v_lshl_add_u64 v[136:137], v[136:137], 0, s[12:13]
	s_addc_u32 s47, s47, 0
	v_mov_b32_e32 v128, v139
	s_add_i32 s91, s94, s73
	global_load_lds_dwordx4 v[136:137], off
	s_mov_b32 m0, s91
	s_nop 0
	global_load_lds_dwordx4 v128, s[46:47]
	v_mov_b32_e32 v128, v141
	s_add_i32 m0, s91, 0x2000
	s_nop 0
	global_load_lds_dwordx4 v128, s[46:47]
	v_mov_b32_e32 v128, v138
	s_mov_b32 m0, s79
	v_lshl_add_u64 v[136:137], s[44:45], 0, v[128:129]
	v_lshl_add_u64 v[136:137], v[136:137], 0, s[12:13]
	v_mov_b32_e32 v128, v140
	global_load_lds_dwordx4 v[136:137], off
	s_mov_b32 m0, s80
	v_lshl_add_u64 v[136:137], s[44:45], 0, v[128:129]
	v_lshl_add_u64 v[136:137], v[136:137], 0, s[12:13]
	global_load_lds_dwordx4 v[136:137], off
	s_waitcnt vmcnt(8)
	s_waitcnt lgkmcnt(0)
	s_barrier
	s_waitcnt lgkmcnt(0)
	v_mfma_i32_16x16x64_i8 v[60:63], v[132:135], v[174:177], v[60:63]
	v_mfma_i32_16x16x64_i8 v[56:59], v[150:153], v[174:177], v[56:59]
	v_mfma_i32_16x16x64_i8 v[44:47], v[132:135], v[182:185], v[44:47]
	v_mfma_i32_16x16x64_i8 v[40:43], v[150:153], v[182:185], v[40:43]
	v_mfma_i32_16x16x64_i8 v[28:31], v[132:135], v[190:193], v[28:31]
	v_mfma_i32_16x16x64_i8 v[24:27], v[150:153], v[190:193], v[24:27]
	v_mfma_i32_16x16x64_i8 v[12:15], v[132:135], v[198:201], v[12:15]
	v_mfma_i32_16x16x64_i8 v[8:11], v[150:153], v[198:201], v[8:11]
	v_mfma_i32_16x16x64_i8 v[60:63], v[146:149], v[178:181], v[60:63]
	v_mfma_i32_16x16x64_i8 v[56:59], v[154:157], v[178:181], v[56:59]
	v_mfma_i32_16x16x64_i8 v[44:47], v[146:149], v[186:189], v[44:47]
	v_mfma_i32_16x16x64_i8 v[40:43], v[154:157], v[186:189], v[40:43]
	v_mfma_i32_16x16x64_i8 v[28:31], v[146:149], v[194:197], v[28:31]
	v_mfma_i32_16x16x64_i8 v[24:27], v[154:157], v[194:197], v[24:27]
	v_mfma_i32_16x16x64_i8 v[12:15], v[146:149], v[202:205], v[12:15]
	v_mfma_i32_16x16x64_i8 v[8:11], v[154:157], v[202:205], v[8:11]
	v_mfma_i32_16x16x64_i8 v[52:55], v[158:161], v[174:177], v[52:55]
	v_mfma_i32_16x16x64_i8 v[48:51], v[166:169], v[174:177], v[48:51]
	v_mfma_i32_16x16x64_i8 v[36:39], v[158:161], v[182:185], v[36:39]
	v_mfma_i32_16x16x64_i8 v[32:35], v[166:169], v[182:185], v[32:35]
	v_mfma_i32_16x16x64_i8 v[20:23], v[158:161], v[190:193], v[20:23]
	v_mfma_i32_16x16x64_i8 v[16:19], v[166:169], v[190:193], v[16:19]
	v_mfma_i32_16x16x64_i8 v[4:7], v[158:161], v[198:201], v[4:7]
	v_mfma_i32_16x16x64_i8 v[0:3], v[166:169], v[198:201], v[0:3]
	v_mfma_i32_16x16x64_i8 v[52:55], v[162:165], v[178:181], v[52:55]
	v_mfma_i32_16x16x64_i8 v[48:51], v[170:173], v[178:181], v[48:51]
	v_mfma_i32_16x16x64_i8 v[36:39], v[162:165], v[186:189], v[36:39]
	v_mfma_i32_16x16x64_i8 v[32:35], v[170:173], v[186:189], v[32:35]
	v_mfma_i32_16x16x64_i8 v[20:23], v[162:165], v[194:197], v[20:23]
	v_mfma_i32_16x16x64_i8 v[16:19], v[170:173], v[194:197], v[16:19]
	v_mfma_i32_16x16x64_i8 v[4:7], v[162:165], v[202:205], v[4:7]
	v_mfma_i32_16x16x64_i8 v[0:3], v[170:173], v[202:205], v[0:3]
	s_barrier
	s_add_i32 s89, s89, 2
	s_add_u32 s8, s8, 0x100
	s_addc_u32 s9, s9, 0
	s_add_u32 s63, s63, 0x100
	s_addc_u32 s88, s88, 0
	s_cmp_gt_u32 s89, 13
	s_cbranch_scc0 .LBB0_421
	s_setprio 0
	s_and_b64 vcc, exec, s[16:17]
	s_cbranch_vccz .LBB0_424
	s_barrier

; #define PG8_STAGE(bufoff, gbase, voff) do { _Pragma("unroll") for (int _i = 0; _i < 2; ++_i) { unsigned _vo = (voff)[_i]; asm volatile("" : "+v"(_vo));   \
;         __builtin_amdgcn_global_load_lds((const unsigned*)((const char*)(gbase) + _vo), (LAS unsigned*)(lds + (bufoff) + ldsw + _i * 8192), 16, 0, 0); } } while (0)
; #define PG8_LDA(dst, b, h) do { _Pragma("unroll") for (int m = 0; m < 4; ++m) _Pragma("unroll") for (int k = 0; k < 2; ++k) dst[m][k] = *(const LAS bf16x8*)(lds + PG8_SA(b, h) + aoff + m * 2048 + k * 1024); } while (0)
; #define PG8_LDB(dst, b, h) do { _Pragma("unroll") for (int n = 0; n < 2; ++n) _Pragma("unroll") for (int k = 0; k < 2; ++k) dst[n][k] = *(const LAS bf16x8*)(lds + PG8_SB(b, h) + boff + n * 2048 + k * 1024); } while (0)
; #define PG8_WAIT_V(n) asm volatile("s_waitcnt vmcnt(" #n ")" ::: "memory")
; #define PG8_WAIT_L(n) asm volatile("s_waitcnt lgkmcnt(" #n ")" ::: "memory")
; #define PG8_BAR __builtin_amdgcn_s_barrier()
; #define PG8_SCHED __builtin_amdgcn_sched_barrier(0)
; template <bool F8 = false>
; __device__ __forceinline__ void gemm_phase(LAS unsigned char* lds, const int K, const Sched& S, const Epi& E, const int wave_s) {
;     ...
;             PG8_LDB(B0, 0, 0); PG8_LDB(B1, 0, 1); PG8_SCHED; PG8_LDA(At, 0, 0); PG8_STAGE(PG8_SA(1, 1), a1 + hstepA, voffA);
;             PG8_WAIT_V(8); PG8_WAIT_L(0); PG8_BAR; PG8_MMA(0, 0, At, B0); PG8_MMA(0, 1, At, B1); PG8_BAR; PG8_SCHED;
;             PG8_LDA(At, 0, 1); PG8_STAGE(PG8_SB(0, 0), b2, voffB); PG8_STAGE(PG8_SB(0, 1), b2 + hstepB, voffB); PG8_STAGE(PG8_SA(0, 0), a2, voffA);
;             PG8_WAIT_V(8); PG8_WAIT_L(0); PG8_BAR; PG8_MMA(1, 0, At, B0); PG8_MMA(1, 1, At, B1); PG8_BAR; PG8_SCHED;
.Lmy_prio1:
	ds_read_b128 v[142:145], v139
	ds_read_b128 v[146:149], v139 offset:1024
	ds_read_b128 v[150:153], v139 offset:2048
	ds_read_b128 v[154:157], v139 offset:3072
	ds_read_b128 v[158:161], v140
	ds_read_b128 v[162:165], v140 offset:1024
	ds_read_b128 v[166:169], v140 offset:2048
	ds_read_b128 v[170:173], v140 offset:3072
	s_add_u32 s42, s40, 0xfffd0080
	s_addc_u32 s43, s41, -1
	s_cmp_eq_u32 s83, 4
	s_cselect_b32 s43, s37, s43
	s_cselect_b32 s42, s36, s42
	s_cselect_b32 s45, s39, s82
	s_cselect_b32 s44, s38, s11
	v_mov_b32_e32 v128, v134
	s_mov_b32 m0, s79
	ds_read_b128 v[174:177], v141
	ds_read_b128 v[178:181], v141 offset:1024
	ds_read_b128 v[182:185], v141 offset:2048
	ds_read_b128 v[186:189], v141 offset:3072
	ds_read_b128 v[190:193], v141 offset:4096
	ds_read_b128 v[194:197], v141 offset:5120
	ds_read_b128 v[198:201], v141 offset:6144
	ds_read_b128 v[202:205], v141 offset:7168
	s_nop 0
	global_load_lds_dwordx4 v128, s[40:41]
	v_mov_b32_e32 v128, v136
	s_mov_b32 m0, s80
	s_nop 0
	global_load_lds_dwordx4 v128, s[40:41]
	s_waitcnt vmcnt(8)
	s_waitcnt lgkmcnt(0)
	s_barrier
	s_waitcnt lgkmcnt(0)
	v_mfma_f32_16x16x32_bf16 v[124:127], v[142:145], v[174:177], v[124:127]
	v_mfma_f32_16x16x32_bf16 v[120:123], v[150:153], v[174:177], v[120:123]
	v_mfma_f32_16x16x32_bf16 v[116:119], v[142:145], v[182:185], v[116:119]
	v_mfma_f32_16x16x32_bf16 v[112:115], v[150:153], v[182:185], v[112:115]
	v_mfma_f32_16x16x32_bf16 v[104:107], v[142:145], v[190:193], v[104:107]
	v_mfma_f32_16x16x32_bf16 v[96:99], v[150:153], v[190:193], v[96:99]
	v_mfma_f32_16x16x32_bf16 v[88:91], v[142:145], v[198:201], v[88:91]
	v_mfma_f32_16x16x32_bf16 v[80:83], v[150:153], v[198:201], v[80:83]
	v_mfma_f32_16x16x32_bf16 v[124:127], v[146:149], v[178:181], v[124:127]
	v_mfma_f32_16x16x32_bf16 v[120:123], v[154:157], v[178:181], v[120:123]
	v_mfma_f32_16x16x32_bf16 v[116:119], v[146:149], v[186:189], v[116:119]
	v_mfma_f32_16x16x32_bf16 v[112:115], v[154:157], v[186:189], v[112:115]
	v_mfma_f32_16x16x32_bf16 v[104:107], v[146:149], v[194:197], v[104:107]
	v_mfma_f32_16x16x32_bf16 v[96:99], v[154:157], v[194:197], v[96:99]
	v_mfma_f32_16x16x32_bf16 v[88:91], v[146:149], v[202:205], v[88:91]
	v_mfma_f32_16x16x32_bf16 v[80:83], v[154:157], v[202:205], v[80:83]
	v_mfma_f32_16x16x32_bf16 v[108:111], v[158:161], v[174:177], v[108:111]
	v_mfma_f32_16x16x32_bf16 v[100:103], v[166:169], v[174:177], v[100:103]
	v_mfma_f32_16x16x32_bf16 v[92:95], v[158:161], v[182:185], v[92:95]
	v_mfma_f32_16x16x32_bf16 v[84:87], v[166:169], v[182:185], v[84:87]
	v_mfma_f32_16x16x32_bf16 v[76:79], v[158:161], v[190:193], v[76:79]
	v_mfma_f32_16x16x32_bf16 v[72:75], v[166:169], v[190:193], v[72:75]
	v_mfma_f32_16x16x32_bf16 v[68:71], v[158:161], v[198:201], v[68:71]
	v_mfma_f32_16x16x32_bf16 v[60:63], v[166:169], v[198:201], v[60:63]
	v_mfma_f32_16x16x32_bf16 v[108:111], v[162:165], v[178:181], v[108:111]
	v_mfma_f32_16x16x32_bf16 v[100:103], v[170:173], v[178:181], v[100:103]
	v_mfma_f32_16x16x32_bf16 v[92:95], v[162:165], v[186:189], v[92:95]
	v_mfma_f32_16x16x32_bf16 v[84:87], v[170:173], v[186:189], v[84:87]
	v_mfma_f32_16x16x32_bf16 v[76:79], v[162:165], v[194:197], v[76:79]
	v_mfma_f32_16x16x32_bf16 v[72:75], v[170:173], v[194:197], v[72:75]
	v_mfma_f32_16x16x32_bf16 v[68:71], v[162:165], v[202:205], v[68:71]
	v_mfma_f32_16x16x32_bf16 v[60:63], v[170:173], v[202:205], v[60:63]
	s_barrier
	v_mov_b32_e32 v128, v135
	s_add_i32 s84, s63, s73
	ds_read_b128 v[174:177], v141 offset:16384
	ds_read_b128 v[178:181], v141 offset:17408
	ds_read_b128 v[182:185], v141 offset:18432
	ds_read_b128 v[186:189], v141 offset:19456
	ds_read_b128 v[190:193], v141 offset:20480
	ds_read_b128 v[194:197], v141 offset:21504
	ds_read_b128 v[198:201], v141 offset:22528
	ds_read_b128 v[202:205], v141 offset:23552
	s_mov_b32 m0, s84
	s_nop 0
	global_load_lds_dwordx4 v128, s[44:45]
	v_mov_b32_e32 v128, v137
	s_add_i32 m0, s84, 0x2000
	s_add_u32 s84, s44, 0x20000
	global_load_lds_dwordx4 v128, s[44:45]
	s_addc_u32 s85, s45, 0
	v_mov_b32_e32 v128, v135
	s_add_i32 s86, s69, s73
	s_mov_b32 m0, s86
	s_nop 0
	global_load_lds_dwordx4 v128, s[84:85]
	v_mov_b32_e32 v128, v137
	s_add_i32 m0, s86, 0x2000
	s_nop 0
	global_load_lds_dwordx4 v128, s[84:85]
	v_mov_b32_e32 v128, v134
	s_mov_b32 m0, s17
	s_nop 0
	global_load_lds_dwordx4 v128, s[42:43]
	v_mov_b32_e32 v128, v136
	s_mov_b32 m0, s46
	s_nop 0
	global_load_lds_dwordx4 v128, s[42:43]
	s_waitcnt vmcnt(8)
	s_waitcnt lgkmcnt(0)
	s_barrier
	s_waitcnt lgkmcnt(0)
	v_mfma_f32_16x16x32_bf16 v[64:67], v[142:145], v[174:177], v[64:67]
	v_mfma_f32_16x16x32_bf16 v[56:59], v[150:153], v[174:177], v[56:59]
	v_mfma_f32_16x16x32_bf16 v[52:55], v[142:145], v[182:185], v[52:55]
	v_mfma_f32_16x16x32_bf16 v[48:51], v[150:153], v[182:185], v[48:51]
	v_mfma_f32_16x16x32_bf16 v[40:43], v[142:145], v[190:193], v[40:43]
	v_mfma_f32_16x16x32_bf16 v[32:35], v[150:153], v[190:193], v[32:35]
	v_mfma_f32_16x16x32_bf16 v[24:27], v[142:145], v[198:201], v[24:27]
	v_mfma_f32_16x16x32_bf16 v[16:19], v[150:153], v[198:201], v[16:19]
	v_mfma_f32_16x16x32_bf16 v[64:67], v[146:149], v[178:181], v[64:67]
	v_mfma_f32_16x16x32_bf16 v[56:59], v[154:157], v[178:181], v[56:59]
	v_mfma_f32_16x16x32_bf16 v[52:55], v[146:149], v[186:189], v[52:55]
	v_mfma_f32_16x16x32_bf16 v[48:51], v[154:157], v[186:189], v[48:51]
	v_mfma_f32_16x16x32_bf16 v[40:43], v[146:149], v[194:197], v[40:43]
	v_mfma_f32_16x16x32_bf16 v[32:35], v[154:157], v[194:197], v[32:35]
	v_mfma_f32_16x16x32_bf16 v[24:27], v[146:149], v[202:205], v[24:27]
	v_mfma_f32_16x16x32_bf16 v[16:19], v[154:157], v[202:205], v[16:19]
	v_mfma_f32_16x16x32_bf16 v[44:47], v[158:161], v[174:177], v[44:47]
	v_mfma_f32_16x16x32_bf16 v[36:39], v[166:169], v[174:177], v[36:39]
	v_mfma_f32_16x16x32_bf16 v[28:31], v[158:161], v[182:185], v[28:31]
	v_mfma_f32_16x16x32_bf16 v[20:23], v[166:169], v[182:185], v[20:23]
	v_mfma_f32_16x16x32_bf16 v[12:15], v[158:161], v[190:193], v[12:15]
	v_mfma_f32_16x16x32_bf16 v[8:11], v[166:169], v[190:193], v[8:11]
	v_mfma_f32_16x16x32_bf16 v[4:7], v[158:161], v[198:201], v[4:7]
	v_mfma_f32_16x16x32_bf16 v[0:3], v[166:169], v[198:201], v[0:3]
	v_mfma_f32_16x16x32_bf16 v[44:47], v[162:165], v[178:181], v[44:47]
	v_mfma_f32_16x16x32_bf16 v[36:39], v[170:173], v[178:181], v[36:39]
	v_mfma_f32_16x16x32_bf16 v[28:31], v[162:165], v[186:189], v[28:31]
	v_mfma_f32_16x16x32_bf16 v[20:23], v[170:173], v[186:189], v[20:23]
	v_mfma_f32_16x16x32_bf16 v[12:15], v[162:165], v[194:197], v[12:15]
	v_mfma_f32_16x16x32_bf16 v[8:11], v[170:173], v[194:197], v[8:11]
	v_mfma_f32_16x16x32_bf16 v[4:7], v[162:165], v[202:205], v[4:7]
	v_mfma_f32_16x16x32_bf16 v[0:3], v[170:173], v[202:205], v[0:3]
	s_barrier
; #define PG8_STAGE(bufoff, gbase, voff) do { _Pragma("unroll") for (int _i = 0; _i < 2; ++_i) { unsigned _vo = (voff)[_i]; asm volatile("" : "+v"(_vo));   \
;         __builtin_amdgcn_global_load_lds((const unsigned*)((const char*)(gbase) + _vo), (LAS unsigned*)(lds + (bufoff) + ldsw + _i * 8192), 16, 0, 0); } } while (0)
; #define PG8_LDA(dst, b, h) do { _Pragma("unroll") for (int m = 0; m < 4; ++m) _Pragma("unroll") for (int k = 0; k < 2; ++k) dst[m][k] = *(const LAS bf16x8*)(lds + PG8_SA(b, h) + aoff + m * 2048 + k * 1024); } while (0)
; #define PG8_LDB(dst, b, h) do { _Pragma("unroll") for (int n = 0; n < 2; ++n) _Pragma("unroll") for (int k = 0; k < 2; ++k) dst[n][k] = *(const LAS bf16x8*)(lds + PG8_SB(b, h) + boff + n * 2048 + k * 1024); } while (0)
; #define PG8_WAIT_V(n) asm volatile("s_waitcnt vmcnt(" #n ")" ::: "memory")
; #define PG8_WAIT_L(n) asm volatile("s_waitcnt lgkmcnt(" #n ")" ::: "memory")
; #define PG8_BAR __builtin_amdgcn_s_barrier()
; #define PG8_SCHED __builtin_amdgcn_sched_barrier(0)
; template <bool F8 = false>
; __device__ __forceinline__ void gemm_phase(LAS unsigned char* lds, const int K, const Sched& S, const Epi& E, const int wave_s) {
;     ...
;             PG8_LDB(B0, 1, 0); PG8_LDB(B1, 1, 1); PG8_SCHED; PG8_LDA(At, 1, 0); PG8_STAGE(PG8_SA(0, 1), a2 + hstepA, voffA);
;             PG8_WAIT_V(8); PG8_WAIT_L(0); PG8_BAR; PG8_MMA(0, 0, At, B0); PG8_MMA(0, 1, At, B1); PG8_BAR; PG8_SCHED;
;             PG8_LDA(At, 1, 1); PG8_STAGE(PG8_SB(1, 0), b3, voffB); PG8_STAGE(PG8_SB(1, 1), b3 + hstepB, voffB); PG8_STAGE(PG8_SA(1, 0), a3, voffA);
;             PG8_WAIT_V(8); PG8_WAIT_L(0); PG8_BAR; PG8_MMA(1, 0, At, B0); PG8_MMA(1, 1, At, B1); PG8_BAR; PG8_SCHED;
	s_add_i32 s86, 0, 0x18000
	v_add_u32_e32 v128, s86, v138
	s_add_i32 s87, 0, 0x1c000
	ds_read_b128 v[142:145], v128
	ds_read_b128 v[146:149], v128 offset:1024
	ds_read_b128 v[150:153], v128 offset:2048
	ds_read_b128 v[154:157], v128 offset:3072
	v_add_u32_e32 v128, s87, v138
	ds_read_b128 v[158:161], v128
	ds_read_b128 v[162:165], v128 offset:1024
	ds_read_b128 v[166:169], v128 offset:2048
	ds_read_b128 v[170:173], v128 offset:3072
	s_add_u32 s84, s42, 0x30000
	v_mov_b32_e32 v128, v134
	s_mov_b32 m0, s47
	ds_read_b128 v[174:177], v141 offset:32768
	ds_read_b128 v[178:181], v141 offset:33792
	ds_read_b128 v[182:185], v141 offset:34816
	ds_read_b128 v[186:189], v141 offset:35840
	ds_read_b128 v[190:193], v141 offset:36864
	ds_read_b128 v[194:197], v141 offset:37888
	ds_read_b128 v[198:201], v141 offset:38912
	ds_read_b128 v[202:205], v141 offset:39936
	s_addc_u32 s85, s43, 0
	s_nop 0
	global_load_lds_dwordx4 v128, s[84:85]
	v_mov_b32_e32 v128, v136
	s_mov_b32 m0, s48
	s_nop 0
	global_load_lds_dwordx4 v128, s[84:85]
	s_waitcnt vmcnt(8)
	s_waitcnt lgkmcnt(0)
	s_barrier
	s_waitcnt lgkmcnt(0)
	v_mfma_f32_16x16x32_bf16 v[124:127], v[142:145], v[174:177], v[124:127]
	v_mfma_f32_16x16x32_bf16 v[120:123], v[150:153], v[174:177], v[120:123]
	v_mfma_f32_16x16x32_bf16 v[116:119], v[142:145], v[182:185], v[116:119]
	v_mfma_f32_16x16x32_bf16 v[112:115], v[150:153], v[182:185], v[112:115]
	v_mfma_f32_16x16x32_bf16 v[104:107], v[142:145], v[190:193], v[104:107]
	v_mfma_f32_16x16x32_bf16 v[96:99], v[150:153], v[190:193], v[96:99]
	v_mfma_f32_16x16x32_bf16 v[88:91], v[142:145], v[198:201], v[88:91]
	v_mfma_f32_16x16x32_bf16 v[80:83], v[150:153], v[198:201], v[80:83]
	v_mfma_f32_16x16x32_bf16 v[124:127], v[146:149], v[178:181], v[124:127]
	v_mfma_f32_16x16x32_bf16 v[120:123], v[154:157], v[178:181], v[120:123]
	v_mfma_f32_16x16x32_bf16 v[116:119], v[146:149], v[186:189], v[116:119]
	v_mfma_f32_16x16x32_bf16 v[112:115], v[154:157], v[186:189], v[112:115]
	v_mfma_f32_16x16x32_bf16 v[104:107], v[146:149], v[194:197], v[104:107]
	v_mfma_f32_16x16x32_bf16 v[96:99], v[154:157], v[194:197], v[96:99]
	v_mfma_f32_16x16x32_bf16 v[88:91], v[146:149], v[202:205], v[88:91]
	v_mfma_f32_16x16x32_bf16 v[80:83], v[154:157], v[202:205], v[80:83]
	v_mfma_f32_16x16x32_bf16 v[108:111], v[158:161], v[174:177], v[108:111]
	v_mfma_f32_16x16x32_bf16 v[100:103], v[166:169], v[174:177], v[100:103]
	v_mfma_f32_16x16x32_bf16 v[92:95], v[158:161], v[182:185], v[92:95]
	v_mfma_f32_16x16x32_bf16 v[84:87], v[166:169], v[182:185], v[84:87]
	v_mfma_f32_16x16x32_bf16 v[76:79], v[158:161], v[190:193], v[76:79]
	v_mfma_f32_16x16x32_bf16 v[72:75], v[166:169], v[190:193], v[72:75]
	v_mfma_f32_16x16x32_bf16 v[68:71], v[158:161], v[198:201], v[68:71]
	v_mfma_f32_16x16x32_bf16 v[60:63], v[166:169], v[198:201], v[60:63]
	v_mfma_f32_16x16x32_bf16 v[108:111], v[162:165], v[178:181], v[108:111]
	v_mfma_f32_16x16x32_bf16 v[100:103], v[170:173], v[178:181], v[100:103]
	v_mfma_f32_16x16x32_bf16 v[92:95], v[162:165], v[186:189], v[92:95]
	v_mfma_f32_16x16x32_bf16 v[84:87], v[170:173], v[186:189], v[84:87]
	v_mfma_f32_16x16x32_bf16 v[76:79], v[162:165], v[194:197], v[76:79]
	v_mfma_f32_16x16x32_bf16 v[72:75], v[170:173], v[194:197], v[72:75]
	v_mfma_f32_16x16x32_bf16 v[68:71], v[162:165], v[202:205], v[68:71]
	v_mfma_f32_16x16x32_bf16 v[60:63], v[170:173], v[202:205], v[60:63]
	s_barrier
; #define PG8_STAGE(bufoff, gbase, voff) do { _Pragma("unroll") for (int _i = 0; _i < 2; ++_i) { unsigned _vo = (voff)[_i]; asm volatile("" : "+v"(_vo));   \
;         __builtin_amdgcn_global_load_lds((const unsigned*)((const char*)(gbase) + _vo), (LAS unsigned*)(lds + (bufoff) + ldsw + _i * 8192), 16, 0, 0); } } while (0)
; #define PG8_LDA(dst, b, h) do { _Pragma("unroll") for (int m = 0; m < 4; ++m) _Pragma("unroll") for (int k = 0; k < 2; ++k) dst[m][k] = *(const LAS bf16x8*)(lds + PG8_SA(b, h) + aoff + m * 2048 + k * 1024); } while (0)
; #define PG8_LDB(dst, b, h) do { _Pragma("unroll") for (int n = 0; n < 2; ++n) _Pragma("unroll") for (int k = 0; k < 2; ++k) dst[n][k] = *(const LAS bf16x8*)(lds + PG8_SB(b, h) + boff + n * 2048 + k * 1024); } while (0)
; #define PG8_WAIT_V(n) asm volatile("s_waitcnt vmcnt(" #n ")" ::: "memory")
; #define PG8_WAIT_L(n) asm volatile("s_waitcnt lgkmcnt(" #n ")" ::: "memory")
; #define PG8_BAR __builtin_amdgcn_s_barrier()
; #define PG8_SCHED __builtin_amdgcn_sched_barrier(0)
; template <bool F8 = false>
; __device__ __forceinline__ void gemm_phase(LAS unsigned char* lds, const int K, const Sched& S, const Epi& E, const int wave_s) {
;     ...
;             PG8_LDB(B0, 1, 0); PG8_LDB(B1, 1, 1); PG8_SCHED; PG8_LDA(At, 1, 0); PG8_STAGE(PG8_SA(0, 1), a2 + hstepA, voffA);
;             PG8_WAIT_V(8); PG8_WAIT_L(0); PG8_BAR; PG8_MMA(0, 0, At, B0); PG8_MMA(0, 1, At, B1); PG8_BAR; PG8_SCHED;
;             PG8_LDA(At, 1, 1); PG8_STAGE(PG8_SB(1, 0), b3, voffB); PG8_STAGE(PG8_SB(1, 1), b3 + hstepB, voffB); PG8_STAGE(PG8_SA(1, 0), a3, voffA);
;             PG8_WAIT_V(8); PG8_WAIT_L(0); PG8_BAR; PG8_MMA(1, 0, At, B0); PG8_MMA(1, 1, At, B1); PG8_BAR; PG8_SCHED;
;         }
	v_mov_b32_e32 v128, v135
	ds_read_b128 v[174:177], v141 offset:49152
	ds_read_b128 v[178:181], v141 offset:50176
	ds_read_b128 v[182:185], v141 offset:51200
	ds_read_b128 v[186:189], v141 offset:52224
	ds_read_b128 v[190:193], v141 offset:53248
	ds_read_b128 v[194:197], v141 offset:54272
	ds_read_b128 v[198:201], v141 offset:55296
	ds_read_b128 v[202:205], v141 offset:56320
	s_add_i32 s84, s86, s73
	v_lshl_add_u64 v[206:207], s[44:45], 0, v[128:129]
	v_lshl_add_u64 v[206:207], v[206:207], 0, s[12:13]
	s_mov_b32 m0, s84
	v_mov_b32_e32 v128, v137
	global_load_lds_dwordx4 v[206:207], off
	s_add_i32 m0, s84, 0x2000
	s_nop 0
	v_lshl_add_u64 v[206:207], s[44:45], 0, v[128:129]
	s_add_u32 s44, s44, 0x20080
	v_lshl_add_u64 v[206:207], v[206:207], 0, s[12:13]
	s_addc_u32 s45, s45, 0
	v_mov_b32_e32 v128, v135
	s_add_i32 s84, s87, s73
	global_load_lds_dwordx4 v[206:207], off
	s_mov_b32 m0, s84
	s_nop 0
	global_load_lds_dwordx4 v128, s[44:45]
	v_mov_b32_e32 v128, v137
	s_add_i32 m0, s84, 0x2000
	s_nop 0
	global_load_lds_dwordx4 v128, s[44:45]
	v_mov_b32_e32 v128, v134
	s_mov_b32 m0, s49
	v_lshl_add_u64 v[206:207], s[42:43], 0, v[128:129]
	v_lshl_add_u64 v[206:207], v[206:207], 0, s[12:13]
	v_mov_b32_e32 v128, v136
	global_load_lds_dwordx4 v[206:207], off
	s_mov_b32 m0, s61
	v_lshl_add_u64 v[206:207], s[42:43], 0, v[128:129]
	v_lshl_add_u64 v[206:207], v[206:207], 0, s[12:13]
	global_load_lds_dwordx4 v[206:207], off
	s_waitcnt vmcnt(8)
	s_waitcnt lgkmcnt(0)
	s_barrier
	s_waitcnt lgkmcnt(0)
	v_mfma_f32_16x16x32_bf16 v[64:67], v[142:145], v[174:177], v[64:67]
	v_mfma_f32_16x16x32_bf16 v[56:59], v[150:153], v[174:177], v[56:59]
	v_mfma_f32_16x16x32_bf16 v[52:55], v[142:145], v[182:185], v[52:55]
	v_mfma_f32_16x16x32_bf16 v[48:51], v[150:153], v[182:185], v[48:51]
	v_mfma_f32_16x16x32_bf16 v[40:43], v[142:145], v[190:193], v[40:43]
	v_mfma_f32_16x16x32_bf16 v[32:35], v[150:153], v[190:193], v[32:35]
	v_mfma_f32_16x16x32_bf16 v[24:27], v[142:145], v[198:201], v[24:27]
	v_mfma_f32_16x16x32_bf16 v[16:19], v[150:153], v[198:201], v[16:19]
	v_mfma_f32_16x16x32_bf16 v[64:67], v[146:149], v[178:181], v[64:67]
	v_mfma_f32_16x16x32_bf16 v[56:59], v[154:157], v[178:181], v[56:59]
	v_mfma_f32_16x16x32_bf16 v[52:55], v[146:149], v[186:189], v[52:55]
	v_mfma_f32_16x16x32_bf16 v[48:51], v[154:157], v[186:189], v[48:51]
	v_mfma_f32_16x16x32_bf16 v[40:43], v[146:149], v[194:197], v[40:43]
	v_mfma_f32_16x16x32_bf16 v[32:35], v[154:157], v[194:197], v[32:35]
	v_mfma_f32_16x16x32_bf16 v[24:27], v[146:149], v[202:205], v[24:27]
	v_mfma_f32_16x16x32_bf16 v[16:19], v[154:157], v[202:205], v[16:19]
	v_mfma_f32_16x16x32_bf16 v[44:47], v[158:161], v[174:177], v[44:47]
	v_mfma_f32_16x16x32_bf16 v[36:39], v[166:169], v[174:177], v[36:39]
	v_mfma_f32_16x16x32_bf16 v[28:31], v[158:161], v[182:185], v[28:31]
	v_mfma_f32_16x16x32_bf16 v[20:23], v[166:169], v[182:185], v[20:23]
	v_mfma_f32_16x16x32_bf16 v[12:15], v[158:161], v[190:193], v[12:15]
	v_mfma_f32_16x16x32_bf16 v[8:11], v[166:169], v[190:193], v[8:11]
	v_mfma_f32_16x16x32_bf16 v[4:7], v[158:161], v[198:201], v[4:7]
	v_mfma_f32_16x16x32_bf16 v[0:3], v[166:169], v[198:201], v[0:3]
	v_mfma_f32_16x16x32_bf16 v[44:47], v[162:165], v[178:181], v[44:47]
	v_mfma_f32_16x16x32_bf16 v[36:39], v[170:173], v[178:181], v[36:39]
	v_mfma_f32_16x16x32_bf16 v[28:31], v[162:165], v[186:189], v[28:31]
	v_mfma_f32_16x16x32_bf16 v[20:23], v[170:173], v[186:189], v[20:23]
	v_mfma_f32_16x16x32_bf16 v[12:15], v[162:165], v[194:197], v[12:15]
	v_mfma_f32_16x16x32_bf16 v[8:11], v[170:173], v[194:197], v[8:11]
	v_mfma_f32_16x16x32_bf16 v[4:7], v[162:165], v[202:205], v[4:7]
	v_mfma_f32_16x16x32_bf16 v[0:3], v[170:173], v[202:205], v[0:3]
	s_barrier
	s_add_i32 s83, s83, 2
	s_add_u32 s40, s40, 0x100
	s_addc_u32 s41, s41, 0
	s_add_u32 s11, s11, 0x100
	s_addc_u32 s82, s82, 0
	s_cmp_gt_u32 s83, 5
	s_cbranch_scc0 .LBB0_651
	s_setprio 0
	s_and_b64 vcc, exec, s[18:19]
	s_cbranch_vccz .LBB0_654
	s_barrier

; #define PG8_STAGE(bufoff, gbase, voff) do { _Pragma("unroll") for (int _i = 0; _i < 2; ++_i) { unsigned _vo = (voff)[_i]; asm volatile("" : "+v"(_vo));   \
;         __builtin_amdgcn_global_load_lds((const unsigned*)((const char*)(gbase) + _vo), (LAS unsigned*)(lds + (bufoff) + ldsw + _i * 8192), 16, 0, 0); } } while (0)
; #define PG8_LDA(dst, b, h) do { _Pragma("unroll") for (int m = 0; m < 4; ++m) _Pragma("unroll") for (int k = 0; k < 2; ++k) dst[m][k] = *(const LAS bf16x8*)(lds + PG8_SA(b, h) + aoff + m * 2048 + k * 1024); } while (0)
; #define PG8_LDB(dst, b, h) do { _Pragma("unroll") for (int n = 0; n < 2; ++n) _Pragma("unroll") for (int k = 0; k < 2; ++k) dst[n][k] = *(const LAS bf16x8*)(lds + PG8_SB(b, h) + boff + n * 2048 + k * 1024); } while (0)
; #define PG8_WAIT_V(n) asm volatile("s_waitcnt vmcnt(" #n ")" ::: "memory")
; #define PG8_WAIT_L(n) asm volatile("s_waitcnt lgkmcnt(" #n ")" ::: "memory")
; #define PG8_BAR __builtin_amdgcn_s_barrier()
; #define PG8_SCHED __builtin_amdgcn_sched_barrier(0)
; template <bool F8 = false>
; __device__ __forceinline__ void gemm_phase(LAS unsigned char* lds, const int K, const Sched& S, const Epi& E, const int wave_s) {
;     ...
;             PG8_LDB(B0, 0, 0); PG8_LDB(B1, 0, 1); PG8_SCHED; PG8_LDA(At, 0, 0); PG8_STAGE(PG8_SA(1, 1), a1 + hstepA, voffA);
;             PG8_WAIT_V(8); PG8_WAIT_L(0); PG8_BAR; PG8_MMA(0, 0, At, B0); PG8_MMA(0, 1, At, B1); PG8_BAR; PG8_SCHED;
;             PG8_LDA(At, 0, 1); PG8_STAGE(PG8_SB(0, 0), b2, voffB); PG8_STAGE(PG8_SB(0, 1), b2 + hstepB, voffB); PG8_STAGE(PG8_SA(0, 0), a2, voffA);
;             PG8_WAIT_V(8); PG8_WAIT_L(0); PG8_BAR; PG8_MMA(1, 0, At, B0); PG8_MMA(1, 1, At, B1); PG8_BAR; PG8_SCHED;
.Lmy_prio2:
	ds_read_b128 v[142:145], v139
	ds_read_b128 v[146:149], v139 offset:1024
	ds_read_b128 v[150:153], v139 offset:2048
	ds_read_b128 v[154:157], v139 offset:3072
	ds_read_b128 v[158:161], v140
	ds_read_b128 v[162:165], v140 offset:1024
	ds_read_b128 v[166:169], v140 offset:2048
	ds_read_b128 v[170:173], v140 offset:3072
	s_add_u32 s40, s38, 0xfffd0080
	s_addc_u32 s41, s39, -1
	s_cmp_eq_u32 s89, 8
	s_cselect_b32 s41, s35, s41
	s_cselect_b32 s40, s34, s40
	s_cselect_b32 s43, s37, s88
	s_cselect_b32 s42, s36, s87
	v_mov_b32_e32 v128, v134
	ds_read_b128 v[174:177], v141
	ds_read_b128 v[178:181], v141 offset:1024
	ds_read_b128 v[182:185], v141 offset:2048
	ds_read_b128 v[186:189], v141 offset:3072
	ds_read_b128 v[190:193], v141 offset:4096
	ds_read_b128 v[194:197], v141 offset:5120
	ds_read_b128 v[198:201], v141 offset:6144
	ds_read_b128 v[202:205], v141 offset:7168
	s_add_i32 m0, s61, 0xc000
	s_nop 0
	global_load_lds_dwordx4 v128, s[38:39]
	v_mov_b32_e32 v128, v136
	s_add_i32 m0, s61, 0xe000
	s_nop 0
	global_load_lds_dwordx4 v128, s[38:39]
	s_waitcnt vmcnt(8)
	s_waitcnt lgkmcnt(0)
	s_barrier
	s_waitcnt lgkmcnt(0)
	v_mfma_f32_16x16x32_bf16 v[124:127], v[142:145], v[174:177], v[124:127]
	v_mfma_f32_16x16x32_bf16 v[120:123], v[150:153], v[174:177], v[120:123]
	v_mfma_f32_16x16x32_bf16 v[108:111], v[142:145], v[182:185], v[108:111]
	v_mfma_f32_16x16x32_bf16 v[104:107], v[150:153], v[182:185], v[104:107]
	v_mfma_f32_16x16x32_bf16 v[92:95], v[142:145], v[190:193], v[92:95]
	v_mfma_f32_16x16x32_bf16 v[88:91], v[150:153], v[190:193], v[88:91]
	v_mfma_f32_16x16x32_bf16 v[76:79], v[142:145], v[198:201], v[76:79]
	v_mfma_f32_16x16x32_bf16 v[72:75], v[150:153], v[198:201], v[72:75]
	v_mfma_f32_16x16x32_bf16 v[124:127], v[146:149], v[178:181], v[124:127]
	v_mfma_f32_16x16x32_bf16 v[120:123], v[154:157], v[178:181], v[120:123]
	v_mfma_f32_16x16x32_bf16 v[108:111], v[146:149], v[186:189], v[108:111]
	v_mfma_f32_16x16x32_bf16 v[104:107], v[154:157], v[186:189], v[104:107]
	v_mfma_f32_16x16x32_bf16 v[92:95], v[146:149], v[194:197], v[92:95]
	v_mfma_f32_16x16x32_bf16 v[88:91], v[154:157], v[194:197], v[88:91]
	v_mfma_f32_16x16x32_bf16 v[76:79], v[146:149], v[202:205], v[76:79]
	v_mfma_f32_16x16x32_bf16 v[72:75], v[154:157], v[202:205], v[72:75]
	v_mfma_f32_16x16x32_bf16 v[116:119], v[158:161], v[174:177], v[116:119]
	v_mfma_f32_16x16x32_bf16 v[112:115], v[166:169], v[174:177], v[112:115]
	v_mfma_f32_16x16x32_bf16 v[100:103], v[158:161], v[182:185], v[100:103]
	v_mfma_f32_16x16x32_bf16 v[96:99], v[166:169], v[182:185], v[96:99]
	v_mfma_f32_16x16x32_bf16 v[84:87], v[158:161], v[190:193], v[84:87]
	v_mfma_f32_16x16x32_bf16 v[80:83], v[166:169], v[190:193], v[80:83]
	v_mfma_f32_16x16x32_bf16 v[68:71], v[158:161], v[198:201], v[68:71]
	v_mfma_f32_16x16x32_bf16 v[64:67], v[166:169], v[198:201], v[64:67]
	v_mfma_f32_16x16x32_bf16 v[116:119], v[162:165], v[178:181], v[116:119]
	v_mfma_f32_16x16x32_bf16 v[112:115], v[170:173], v[178:181], v[112:115]
	v_mfma_f32_16x16x32_bf16 v[100:103], v[162:165], v[186:189], v[100:103]
	v_mfma_f32_16x16x32_bf16 v[96:99], v[170:173], v[186:189], v[96:99]
	v_mfma_f32_16x16x32_bf16 v[84:87], v[162:165], v[194:197], v[84:87]
	v_mfma_f32_16x16x32_bf16 v[80:83], v[170:173], v[194:197], v[80:83]
	v_mfma_f32_16x16x32_bf16 v[68:71], v[162:165], v[202:205], v[68:71]
	v_mfma_f32_16x16x32_bf16 v[64:67], v[170:173], v[202:205], v[64:67]
	s_barrier
	v_mov_b32_e32 v128, v135
	s_add_i32 s90, s83, s73
	ds_read_b128 v[174:177], v141 offset:16384
	ds_read_b128 v[178:181], v141 offset:17408
	ds_read_b128 v[182:185], v141 offset:18432
	ds_read_b128 v[186:189], v141 offset:19456
	ds_read_b128 v[190:193], v141 offset:20480
	ds_read_b128 v[194:197], v141 offset:21504
	ds_read_b128 v[198:201], v141 offset:22528
	ds_read_b128 v[202:205], v141 offset:23552
	s_mov_b32 m0, s90
	s_nop 0
	global_load_lds_dwordx4 v128, s[42:43]
	v_mov_b32_e32 v128, v137
	s_add_i32 m0, s90, 0x2000
	s_add_u32 s90, s42, 0x30000
	global_load_lds_dwordx4 v128, s[42:43]
	s_addc_u32 s91, s43, 0
	v_mov_b32_e32 v128, v135
	s_add_i32 s92, s84, s73
	s_mov_b32 m0, s92
	s_nop 0
	global_load_lds_dwordx4 v128, s[90:91]
	v_mov_b32_e32 v128, v137
	s_add_i32 m0, s92, 0x2000
	s_nop 0
	global_load_lds_dwordx4 v128, s[90:91]
	v_mov_b32_e32 v128, v134
	s_mov_b32 m0, s61
	s_nop 0
	global_load_lds_dwordx4 v128, s[40:41]
	v_mov_b32_e32 v128, v136
	s_mov_b32 m0, s68
	s_nop 0
	global_load_lds_dwordx4 v128, s[40:41]
	s_waitcnt vmcnt(8)
	s_waitcnt lgkmcnt(0)
	s_barrier
	s_waitcnt lgkmcnt(0)
	v_mfma_f32_16x16x32_bf16 v[60:63], v[142:145], v[174:177], v[60:63]
	v_mfma_f32_16x16x32_bf16 v[56:59], v[150:153], v[174:177], v[56:59]
	v_mfma_f32_16x16x32_bf16 v[44:47], v[142:145], v[182:185], v[44:47]
	v_mfma_f32_16x16x32_bf16 v[40:43], v[150:153], v[182:185], v[40:43]
	v_mfma_f32_16x16x32_bf16 v[28:31], v[142:145], v[190:193], v[28:31]
	v_mfma_f32_16x16x32_bf16 v[24:27], v[150:153], v[190:193], v[24:27]
	v_mfma_f32_16x16x32_bf16 v[12:15], v[142:145], v[198:201], v[12:15]
	v_mfma_f32_16x16x32_bf16 v[8:11], v[150:153], v[198:201], v[8:11]
	v_mfma_f32_16x16x32_bf16 v[60:63], v[146:149], v[178:181], v[60:63]
	v_mfma_f32_16x16x32_bf16 v[56:59], v[154:157], v[178:181], v[56:59]
	v_mfma_f32_16x16x32_bf16 v[44:47], v[146:149], v[186:189], v[44:47]
	v_mfma_f32_16x16x32_bf16 v[40:43], v[154:157], v[186:189], v[40:43]
	v_mfma_f32_16x16x32_bf16 v[28:31], v[146:149], v[194:197], v[28:31]
	v_mfma_f32_16x16x32_bf16 v[24:27], v[154:157], v[194:197], v[24:27]
	v_mfma_f32_16x16x32_bf16 v[12:15], v[146:149], v[202:205], v[12:15]
	v_mfma_f32_16x16x32_bf16 v[8:11], v[154:157], v[202:205], v[8:11]
	v_mfma_f32_16x16x32_bf16 v[52:55], v[158:161], v[174:177], v[52:55]
	v_mfma_f32_16x16x32_bf16 v[48:51], v[166:169], v[174:177], v[48:51]
	v_mfma_f32_16x16x32_bf16 v[36:39], v[158:161], v[182:185], v[36:39]
	v_mfma_f32_16x16x32_bf16 v[32:35], v[166:169], v[182:185], v[32:35]
	v_mfma_f32_16x16x32_bf16 v[20:23], v[158:161], v[190:193], v[20:23]
	v_mfma_f32_16x16x32_bf16 v[16:19], v[166:169], v[190:193], v[16:19]
	v_mfma_f32_16x16x32_bf16 v[4:7], v[158:161], v[198:201], v[4:7]
	v_mfma_f32_16x16x32_bf16 v[0:3], v[166:169], v[198:201], v[0:3]
	v_mfma_f32_16x16x32_bf16 v[52:55], v[162:165], v[178:181], v[52:55]
	v_mfma_f32_16x16x32_bf16 v[48:51], v[170:173], v[178:181], v[48:51]
	v_mfma_f32_16x16x32_bf16 v[36:39], v[162:165], v[186:189], v[36:39]
	v_mfma_f32_16x16x32_bf16 v[32:35], v[170:173], v[186:189], v[32:35]
	v_mfma_f32_16x16x32_bf16 v[20:23], v[162:165], v[194:197], v[20:23]
	v_mfma_f32_16x16x32_bf16 v[16:19], v[170:173], v[194:197], v[16:19]
	v_mfma_f32_16x16x32_bf16 v[4:7], v[162:165], v[202:205], v[4:7]
	v_mfma_f32_16x16x32_bf16 v[0:3], v[170:173], v[202:205], v[0:3]
	s_barrier
; #define PG8_STAGE(bufoff, gbase, voff) do { _Pragma("unroll") for (int _i = 0; _i < 2; ++_i) { unsigned _vo = (voff)[_i]; asm volatile("" : "+v"(_vo));   \
;         __builtin_amdgcn_global_load_lds((const unsigned*)((const char*)(gbase) + _vo), (LAS unsigned*)(lds + (bufoff) + ldsw + _i * 8192), 16, 0, 0); } } while (0)
; #define PG8_LDA(dst, b, h) do { _Pragma("unroll") for (int m = 0; m < 4; ++m) _Pragma("unroll") for (int k = 0; k < 2; ++k) dst[m][k] = *(const LAS bf16x8*)(lds + PG8_SA(b, h) + aoff + m * 2048 + k * 1024); } while (0)
; #define PG8_LDB(dst, b, h) do { _Pragma("unroll") for (int n = 0; n < 2; ++n) _Pragma("unroll") for (int k = 0; k < 2; ++k) dst[n][k] = *(const LAS bf16x8*)(lds + PG8_SB(b, h) + boff + n * 2048 + k * 1024); } while (0)
; #define PG8_WAIT_V(n) asm volatile("s_waitcnt vmcnt(" #n ")" ::: "memory")
; #define PG8_WAIT_L(n) asm volatile("s_waitcnt lgkmcnt(" #n ")" ::: "memory")
; #define PG8_BAR __builtin_amdgcn_s_barrier()
; #define PG8_SCHED __builtin_amdgcn_sched_barrier(0)
; template <bool F8 = false>
; __device__ __forceinline__ void gemm_phase(LAS unsigned char* lds, const int K, const Sched& S, const Epi& E, const int wave_s) {
;     ...
;             PG8_LDB(B0, 1, 0); PG8_LDB(B1, 1, 1); PG8_SCHED; PG8_LDA(At, 1, 0); PG8_STAGE(PG8_SA(0, 1), a2 + hstepA, voffA);
;             PG8_WAIT_V(8); PG8_WAIT_L(0); PG8_BAR; PG8_MMA(0, 0, At, B0); PG8_MMA(0, 1, At, B1); PG8_BAR; PG8_SCHED;
	s_add_i32 s92, 0, 0x18000
	v_add_u32_e32 v128, s92, v138
	s_add_i32 s93, 0, 0x1c000
	ds_read_b128 v[142:145], v128
	ds_read_b128 v[146:149], v128 offset:1024
	ds_read_b128 v[150:153], v128 offset:2048
	ds_read_b128 v[154:157], v128 offset:3072
	v_add_u32_e32 v128, s93, v138
	ds_read_b128 v[158:161], v128
	ds_read_b128 v[162:165], v128 offset:1024
	ds_read_b128 v[166:169], v128 offset:2048
	ds_read_b128 v[170:173], v128 offset:3072
	s_add_u32 s90, s40, 0x30000
	v_mov_b32_e32 v128, v134
	s_mov_b32 m0, s69
	ds_read_b128 v[174:177], v141 offset:32768
	ds_read_b128 v[178:181], v141 offset:33792
	ds_read_b128 v[182:185], v141 offset:34816
	ds_read_b128 v[186:189], v141 offset:35840
	ds_read_b128 v[190:193], v141 offset:36864
	ds_read_b128 v[194:197], v141 offset:37888
	ds_read_b128 v[198:201], v141 offset:38912
	ds_read_b128 v[202:205], v141 offset:39936
	s_addc_u32 s91, s41, 0
	s_nop 0
	global_load_lds_dwordx4 v128, s[90:91]
	v_mov_b32_e32 v128, v136
	s_mov_b32 m0, s79
	s_nop 0
	global_load_lds_dwordx4 v128, s[90:91]
	s_waitcnt vmcnt(8)
	s_waitcnt lgkmcnt(0)
	s_barrier
	s_waitcnt lgkmcnt(0)
	v_mfma_f32_16x16x32_bf16 v[124:127], v[142:145], v[174:177], v[124:127]
	v_mfma_f32_16x16x32_bf16 v[120:123], v[150:153], v[174:177], v[120:123]
	v_mfma_f32_16x16x32_bf16 v[108:111], v[142:145], v[182:185], v[108:111]
	v_mfma_f32_16x16x32_bf16 v[104:107], v[150:153], v[182:185], v[104:107]
	v_mfma_f32_16x16x32_bf16 v[92:95], v[142:145], v[190:193], v[92:95]
	v_mfma_f32_16x16x32_bf16 v[88:91], v[150:153], v[190:193], v[88:91]
	v_mfma_f32_16x16x32_bf16 v[76:79], v[142:145], v[198:201], v[76:79]
	v_mfma_f32_16x16x32_bf16 v[72:75], v[150:153], v[198:201], v[72:75]
	v_mfma_f32_16x16x32_bf16 v[124:127], v[146:149], v[178:181], v[124:127]
	v_mfma_f32_16x16x32_bf16 v[120:123], v[154:157], v[178:181], v[120:123]
	v_mfma_f32_16x16x32_bf16 v[108:111], v[146:149], v[186:189], v[108:111]
	v_mfma_f32_16x16x32_bf16 v[104:107], v[154:157], v[186:189], v[104:107]
	v_mfma_f32_16x16x32_bf16 v[92:95], v[146:149], v[194:197], v[92:95]
	v_mfma_f32_16x16x32_bf16 v[88:91], v[154:157], v[194:197], v[88:91]
	v_mfma_f32_16x16x32_bf16 v[76:79], v[146:149], v[202:205], v[76:79]
	v_mfma_f32_16x16x32_bf16 v[72:75], v[154:157], v[202:205], v[72:75]
	v_mfma_f32_16x16x32_bf16 v[116:119], v[158:161], v[174:177], v[116:119]
	v_mfma_f32_16x16x32_bf16 v[112:115], v[166:169], v[174:177], v[112:115]
	v_mfma_f32_16x16x32_bf16 v[100:103], v[158:161], v[182:185], v[100:103]
	v_mfma_f32_16x16x32_bf16 v[96:99], v[166:169], v[182:185], v[96:99]
	v_mfma_f32_16x16x32_bf16 v[84:87], v[158:161], v[190:193], v[84:87]
	v_mfma_f32_16x16x32_bf16 v[80:83], v[166:169], v[190:193], v[80:83]
	v_mfma_f32_16x16x32_bf16 v[68:71], v[158:161], v[198:201], v[68:71]
	v_mfma_f32_16x16x32_bf16 v[64:67], v[166:169], v[198:201], v[64:67]
	v_mfma_f32_16x16x32_bf16 v[116:119], v[162:165], v[178:181], v[116:119]
	v_mfma_f32_16x16x32_bf16 v[112:115], v[170:173], v[178:181], v[112:115]
	v_mfma_f32_16x16x32_bf16 v[100:103], v[162:165], v[186:189], v[100:103]
	v_mfma_f32_16x16x32_bf16 v[96:99], v[170:173], v[186:189], v[96:99]
	v_mfma_f32_16x16x32_bf16 v[84:87], v[162:165], v[194:197], v[84:87]
	v_mfma_f32_16x16x32_bf16 v[80:83], v[170:173], v[194:197], v[80:83]
	v_mfma_f32_16x16x32_bf16 v[68:71], v[162:165], v[202:205], v[68:71]
	v_mfma_f32_16x16x32_bf16 v[64:67], v[170:173], v[202:205], v[64:67]
	s_barrier
; #define PG8_STAGE(bufoff, gbase, voff) do { _Pragma("unroll") for (int _i = 0; _i < 2; ++_i) { unsigned _vo = (voff)[_i]; asm volatile("" : "+v"(_vo));   \
;         __builtin_amdgcn_global_load_lds((const unsigned*)((const char*)(gbase) + _vo), (LAS unsigned*)(lds + (bufoff) + ldsw + _i * 8192), 16, 0, 0); } } while (0)
; #define PG8_LDA(dst, b, h) do { _Pragma("unroll") for (int m = 0; m < 4; ++m) _Pragma("unroll") for (int k = 0; k < 2; ++k) dst[m][k] = *(const LAS bf16x8*)(lds + PG8_SA(b, h) + aoff + m * 2048 + k * 1024); } while (0)
; #define PG8_WAIT_V(n) asm volatile("s_waitcnt vmcnt(" #n ")" ::: "memory")
; #define PG8_WAIT_L(n) asm volatile("s_waitcnt lgkmcnt(" #n ")" ::: "memory")
; #define PG8_BAR __builtin_amdgcn_s_barrier()
; #define PG8_SCHED __builtin_amdgcn_sched_barrier(0)
; template <bool F8 = false>
; __device__ __forceinline__ void gemm_phase(LAS unsigned char* lds, const int K, const Sched& S, const Epi& E, const int wave_s) {
;     ...
;             PG8_LDA(At, 1, 1); PG8_STAGE(PG8_SB(1, 0), b3, voffB); PG8_STAGE(PG8_SB(1, 1), b3 + hstepB, voffB); PG8_STAGE(PG8_SA(1, 0), a3, voffA);
;             PG8_WAIT_V(8); PG8_WAIT_L(0); PG8_BAR; PG8_MMA(1, 0, At, B0); PG8_MMA(1, 1, At, B1); PG8_BAR; PG8_SCHED;
;         }
;         if (align) { if (wr == 0) PG8_BAR; }
	v_mov_b32_e32 v128, v135
	ds_read_b128 v[174:177], v141 offset:49152
	ds_read_b128 v[178:181], v141 offset:50176
	ds_read_b128 v[182:185], v141 offset:51200
	ds_read_b128 v[186:189], v141 offset:52224
	ds_read_b128 v[190:193], v141 offset:53248
	ds_read_b128 v[194:197], v141 offset:54272
	ds_read_b128 v[198:201], v141 offset:55296
	ds_read_b128 v[202:205], v141 offset:56320
	s_add_i32 s90, s92, s73
	v_lshl_add_u64 v[206:207], s[42:43], 0, v[128:129]
	v_lshl_add_u64 v[206:207], v[206:207], 0, s[8:9]
	s_mov_b32 m0, s90
	v_mov_b32_e32 v128, v137
	global_load_lds_dwordx4 v[206:207], off
	s_add_i32 m0, s90, 0x2000
	s_nop 0
	v_lshl_add_u64 v[206:207], s[42:43], 0, v[128:129]
	s_add_u32 s42, s42, 0x30080
	v_lshl_add_u64 v[206:207], v[206:207], 0, s[8:9]
	s_addc_u32 s43, s43, 0
	v_mov_b32_e32 v128, v135
	s_add_i32 s90, s93, s73
	global_load_lds_dwordx4 v[206:207], off
	s_mov_b32 m0, s90
	s_nop 0
	global_load_lds_dwordx4 v128, s[42:43]
	v_mov_b32_e32 v128, v137
	s_add_i32 m0, s90, 0x2000
	s_nop 0
	global_load_lds_dwordx4 v128, s[42:43]
	v_mov_b32_e32 v128, v134
	s_mov_b32 m0, s81
	v_lshl_add_u64 v[206:207], s[40:41], 0, v[128:129]
	v_lshl_add_u64 v[206:207], v[206:207], 0, s[8:9]
	v_mov_b32_e32 v128, v136
	global_load_lds_dwordx4 v[206:207], off
	s_mov_b32 m0, s82
	v_lshl_add_u64 v[206:207], s[40:41], 0, v[128:129]
	v_lshl_add_u64 v[206:207], v[206:207], 0, s[8:9]
	global_load_lds_dwordx4 v[206:207], off
	s_waitcnt vmcnt(8)
	s_waitcnt lgkmcnt(0)
	s_barrier
	s_waitcnt lgkmcnt(0)
	v_mfma_f32_16x16x32_bf16 v[60:63], v[142:145], v[174:177], v[60:63]
	v_mfma_f32_16x16x32_bf16 v[56:59], v[150:153], v[174:177], v[56:59]
	v_mfma_f32_16x16x32_bf16 v[44:47], v[142:145], v[182:185], v[44:47]
	v_mfma_f32_16x16x32_bf16 v[40:43], v[150:153], v[182:185], v[40:43]
	v_mfma_f32_16x16x32_bf16 v[28:31], v[142:145], v[190:193], v[28:31]
	v_mfma_f32_16x16x32_bf16 v[24:27], v[150:153], v[190:193], v[24:27]
	v_mfma_f32_16x16x32_bf16 v[12:15], v[142:145], v[198:201], v[12:15]
	v_mfma_f32_16x16x32_bf16 v[8:11], v[150:153], v[198:201], v[8:11]
	v_mfma_f32_16x16x32_bf16 v[60:63], v[146:149], v[178:181], v[60:63]
	v_mfma_f32_16x16x32_bf16 v[56:59], v[154:157], v[178:181], v[56:59]
	v_mfma_f32_16x16x32_bf16 v[44:47], v[146:149], v[186:189], v[44:47]
	v_mfma_f32_16x16x32_bf16 v[40:43], v[154:157], v[186:189], v[40:43]
	v_mfma_f32_16x16x32_bf16 v[28:31], v[146:149], v[194:197], v[28:31]
	v_mfma_f32_16x16x32_bf16 v[24:27], v[154:157], v[194:197], v[24:27]
	v_mfma_f32_16x16x32_bf16 v[12:15], v[146:149], v[202:205], v[12:15]
	v_mfma_f32_16x16x32_bf16 v[8:11], v[154:157], v[202:205], v[8:11]
	v_mfma_f32_16x16x32_bf16 v[52:55], v[158:161], v[174:177], v[52:55]
	v_mfma_f32_16x16x32_bf16 v[48:51], v[166:169], v[174:177], v[48:51]
	v_mfma_f32_16x16x32_bf16 v[36:39], v[158:161], v[182:185], v[36:39]
	v_mfma_f32_16x16x32_bf16 v[32:35], v[166:169], v[182:185], v[32:35]
	v_mfma_f32_16x16x32_bf16 v[20:23], v[158:161], v[190:193], v[20:23]
	v_mfma_f32_16x16x32_bf16 v[16:19], v[166:169], v[190:193], v[16:19]
	v_mfma_f32_16x16x32_bf16 v[4:7], v[158:161], v[198:201], v[4:7]
	v_mfma_f32_16x16x32_bf16 v[0:3], v[166:169], v[198:201], v[0:3]
	v_mfma_f32_16x16x32_bf16 v[52:55], v[162:165], v[178:181], v[52:55]
	v_mfma_f32_16x16x32_bf16 v[48:51], v[170:173], v[178:181], v[48:51]
	v_mfma_f32_16x16x32_bf16 v[36:39], v[162:165], v[186:189], v[36:39]
	v_mfma_f32_16x16x32_bf16 v[32:35], v[170:173], v[186:189], v[32:35]
	v_mfma_f32_16x16x32_bf16 v[20:23], v[162:165], v[194:197], v[20:23]
	v_mfma_f32_16x16x32_bf16 v[16:19], v[170:173], v[194:197], v[16:19]
	v_mfma_f32_16x16x32_bf16 v[4:7], v[162:165], v[202:205], v[4:7]
	v_mfma_f32_16x16x32_bf16 v[0:3], v[170:173], v[202:205], v[0:3]
	s_barrier
	s_add_i32 s89, s89, 2
	s_add_u32 s38, s38, 0x100
	s_addc_u32 s39, s39, 0
	s_add_u32 s87, s87, 0x100
	s_addc_u32 s88, s88, 0
	s_cmp_gt_u32 s89, 9
	s_cbranch_scc0 .LBB0_853
	s_setprio 0
	s_and_b64 vcc, exec, s[10:11]
	s_cbranch_vccz .LBB0_856
	s_barrier

; #define PG8_STAGE(bufoff, gbase, voff) do { _Pragma("unroll") for (int _i = 0; _i < 2; ++_i) { unsigned _vo = (voff)[_i]; asm volatile("" : "+v"(_vo));   \
;         __builtin_amdgcn_global_load_lds((const unsigned*)((const char*)(gbase) + _vo), (LAS unsigned*)(lds + (bufoff) + ldsw + _i * 8192), 16, 0, 0); } } while (0)
; #define PG8_LDA(dst, b, h) do { _Pragma("unroll") for (int m = 0; m < 4; ++m) _Pragma("unroll") for (int k = 0; k < 2; ++k) dst[m][k] = *(const LAS bf16x8*)(lds + PG8_SA(b, h) + aoff + m * 2048 + k * 1024); } while (0)
; #define PG8_LDB(dst, b, h) do { _Pragma("unroll") for (int n = 0; n < 2; ++n) _Pragma("unroll") for (int k = 0; k < 2; ++k) dst[n][k] = *(const LAS bf16x8*)(lds + PG8_SB(b, h) + boff + n * 2048 + k * 1024); } while (0)
; #define PG8_WAIT_V(n) asm volatile("s_waitcnt vmcnt(" #n ")" ::: "memory")
; #define PG8_WAIT_L(n) asm volatile("s_waitcnt lgkmcnt(" #n ")" ::: "memory")
; #define PG8_BAR __builtin_amdgcn_s_barrier()
; #define PG8_SCHED __builtin_amdgcn_sched_barrier(0)
; template <bool F8 = false>
; __device__ __forceinline__ void gemm_phase(LAS unsigned char* lds, const int K, const Sched& S, const Epi& E, const int wave_s) {
;     ...
;             PG8_LDB(B0, 0, 0); PG8_LDB(B1, 0, 1); PG8_SCHED; PG8_LDA(At, 0, 0); PG8_STAGE(PG8_SA(1, 1), a1 + hstepA, voffA);
;             PG8_WAIT_V(8); PG8_WAIT_L(0); PG8_BAR; PG8_MMA(0, 0, At, B0); PG8_MMA(0, 1, At, B1); PG8_BAR; PG8_SCHED;
;             PG8_LDA(At, 0, 1); PG8_STAGE(PG8_SB(0, 0), b2, voffB); PG8_STAGE(PG8_SB(0, 1), b2 + hstepB, voffB); PG8_STAGE(PG8_SA(0, 0), a2, voffA);
;             PG8_WAIT_V(8); PG8_WAIT_L(0); PG8_BAR; PG8_MMA(1, 0, At, B0); PG8_MMA(1, 1, At, B1); PG8_BAR; PG8_SCHED;
.Lmy_prio3:
	ds_read_b128 v[112:115], v195
	ds_read_b128 v[128:131], v195 offset:1024
	ds_read_b128 v[136:139], v195 offset:2048
	ds_read_b128 v[140:143], v195 offset:3072
	ds_read_b128 v[144:147], v196
	ds_read_b128 v[148:151], v196 offset:1024
	ds_read_b128 v[152:155], v196 offset:2048
	ds_read_b128 v[156:159], v196 offset:3072
	s_add_u32 s38, s36, 0xfffc0080
	s_addc_u32 s39, s37, -1
	s_cmp_eq_u32 s63, 12
	s_cselect_b32 s39, s31, s39
	s_cselect_b32 s38, s30, s38
	s_cselect_b32 s41, s35, s62
	s_cselect_b32 s40, s34, s13
	v_mov_b32_e32 v172, v190
	ds_read_b128 v[160:163], v197
	ds_read_b128 v[164:167], v197 offset:1024
	ds_read_b128 v[168:171], v197 offset:2048
	ds_read_b128 v[178:181], v197 offset:3072
	ds_read_b128 v[182:185], v197 offset:4096
	ds_read_b128 v[186:189], v197 offset:5120
	ds_read_b128 v[198:201], v197 offset:6144
	ds_read_b128 v[202:205], v197 offset:7168
	s_add_i32 m0, s29, 0xc000
	s_nop 0
	global_load_lds_dwordx4 v172, s[36:37]
	v_mov_b32_e32 v172, v192
	s_add_i32 m0, s29, 0xe000
	s_nop 0
	global_load_lds_dwordx4 v172, s[36:37]
	s_waitcnt vmcnt(8)
	s_waitcnt lgkmcnt(0)
	s_barrier
	s_waitcnt lgkmcnt(0)
	v_mfma_f32_16x16x32_bf16 v[104:107], v[112:115], v[160:163], v[104:107]
	v_mfma_f32_16x16x32_bf16 v[132:135], v[136:139], v[160:163], v[132:135]
	v_mfma_f32_16x16x32_bf16 v[116:119], v[112:115], v[168:171], v[116:119]
	v_mfma_f32_16x16x32_bf16 v[108:111], v[136:139], v[168:171], v[108:111]
	v_mfma_f32_16x16x32_bf16 v[92:95], v[112:115], v[182:185], v[92:95]
	v_mfma_f32_16x16x32_bf16 v[88:91], v[136:139], v[182:185], v[88:91]
	v_mfma_f32_16x16x32_bf16 v[76:79], v[112:115], v[198:201], v[76:79]
	v_mfma_f32_16x16x32_bf16 v[72:75], v[136:139], v[198:201], v[72:75]
	v_mfma_f32_16x16x32_bf16 v[104:107], v[128:131], v[164:167], v[104:107]
	v_mfma_f32_16x16x32_bf16 v[132:135], v[140:143], v[164:167], v[132:135]
	v_mfma_f32_16x16x32_bf16 v[116:119], v[128:131], v[178:181], v[116:119]
	v_mfma_f32_16x16x32_bf16 v[108:111], v[140:143], v[178:181], v[108:111]
	v_mfma_f32_16x16x32_bf16 v[92:95], v[128:131], v[186:189], v[92:95]
	v_mfma_f32_16x16x32_bf16 v[88:91], v[140:143], v[186:189], v[88:91]
	v_mfma_f32_16x16x32_bf16 v[76:79], v[128:131], v[202:205], v[76:79]
	v_mfma_f32_16x16x32_bf16 v[72:75], v[140:143], v[202:205], v[72:75]
	v_mfma_f32_16x16x32_bf16 v[124:127], v[144:147], v[160:163], v[124:127]
	v_mfma_f32_16x16x32_bf16 v[120:123], v[152:155], v[160:163], v[120:123]
	v_mfma_f32_16x16x32_bf16 v[100:103], v[144:147], v[168:171], v[100:103]
	v_mfma_f32_16x16x32_bf16 v[96:99], v[152:155], v[168:171], v[96:99]
	v_mfma_f32_16x16x32_bf16 v[84:87], v[144:147], v[182:185], v[84:87]
	v_mfma_f32_16x16x32_bf16 v[80:83], v[152:155], v[182:185], v[80:83]
	v_mfma_f32_16x16x32_bf16 v[68:71], v[144:147], v[198:201], v[68:71]
	v_mfma_f32_16x16x32_bf16 v[64:67], v[152:155], v[198:201], v[64:67]
	v_mfma_f32_16x16x32_bf16 v[124:127], v[148:151], v[164:167], v[124:127]
	v_mfma_f32_16x16x32_bf16 v[120:123], v[156:159], v[164:167], v[120:123]
	v_mfma_f32_16x16x32_bf16 v[100:103], v[148:151], v[178:181], v[100:103]
	v_mfma_f32_16x16x32_bf16 v[96:99], v[156:159], v[178:181], v[96:99]
	v_mfma_f32_16x16x32_bf16 v[84:87], v[148:151], v[186:189], v[84:87]
	v_mfma_f32_16x16x32_bf16 v[80:83], v[156:159], v[186:189], v[80:83]
	v_mfma_f32_16x16x32_bf16 v[68:71], v[148:151], v[202:205], v[68:71]
	v_mfma_f32_16x16x32_bf16 v[64:67], v[156:159], v[202:205], v[64:67]
	s_barrier
	v_mov_b32_e32 v172, v191
	s_add_i32 s68, s48, s73
	ds_read_b128 v[160:163], v197 offset:16384
	ds_read_b128 v[164:167], v197 offset:17408
	ds_read_b128 v[168:171], v197 offset:18432
	ds_read_b128 v[178:181], v197 offset:19456
	ds_read_b128 v[182:185], v197 offset:20480
	ds_read_b128 v[186:189], v197 offset:21504
	ds_read_b128 v[198:201], v197 offset:22528
	ds_read_b128 v[202:205], v197 offset:23552
	s_mov_b32 m0, s68
	s_nop 0
	global_load_lds_dwordx4 v172, s[40:41]
	v_mov_b32_e32 v172, v193
	s_add_i32 m0, s68, 0x2000
	s_add_u32 s68, s40, 0x40000
	global_load_lds_dwordx4 v172, s[40:41]
	s_addc_u32 s69, s41, 0
	v_mov_b32_e32 v172, v191
	s_add_i32 s79, s49, s73
	s_mov_b32 m0, s79
	s_nop 0
	global_load_lds_dwordx4 v172, s[68:69]
	v_mov_b32_e32 v172, v193
	s_add_i32 m0, s79, 0x2000
	s_nop 0
	global_load_lds_dwordx4 v172, s[68:69]
	v_mov_b32_e32 v172, v190
	s_mov_b32 m0, s29
	s_nop 0
	global_load_lds_dwordx4 v172, s[38:39]
	v_mov_b32_e32 v172, v192
	s_mov_b32 m0, s42
	s_nop 0
	global_load_lds_dwordx4 v172, s[38:39]
	s_waitcnt vmcnt(8)
	s_waitcnt lgkmcnt(0)
	s_barrier
	s_waitcnt lgkmcnt(0)
	v_mfma_f32_16x16x32_bf16 v[60:63], v[112:115], v[160:163], v[60:63]
	v_mfma_f32_16x16x32_bf16 v[56:59], v[136:139], v[160:163], v[56:59]
	v_mfma_f32_16x16x32_bf16 v[44:47], v[112:115], v[168:171], v[44:47]
	v_mfma_f32_16x16x32_bf16 v[40:43], v[136:139], v[168:171], v[40:43]
	v_mfma_f32_16x16x32_bf16 v[28:31], v[112:115], v[182:185], v[28:31]
	v_mfma_f32_16x16x32_bf16 v[24:27], v[136:139], v[182:185], v[24:27]
	v_mfma_f32_16x16x32_bf16 v[12:15], v[112:115], v[198:201], v[12:15]
	v_mfma_f32_16x16x32_bf16 v[8:11], v[136:139], v[198:201], v[8:11]
	v_mfma_f32_16x16x32_bf16 v[60:63], v[128:131], v[164:167], v[60:63]
	v_mfma_f32_16x16x32_bf16 v[56:59], v[140:143], v[164:167], v[56:59]
	v_mfma_f32_16x16x32_bf16 v[44:47], v[128:131], v[178:181], v[44:47]
	v_mfma_f32_16x16x32_bf16 v[40:43], v[140:143], v[178:181], v[40:43]
	v_mfma_f32_16x16x32_bf16 v[28:31], v[128:131], v[186:189], v[28:31]
	v_mfma_f32_16x16x32_bf16 v[24:27], v[140:143], v[186:189], v[24:27]
	v_mfma_f32_16x16x32_bf16 v[12:15], v[128:131], v[202:205], v[12:15]
	v_mfma_f32_16x16x32_bf16 v[8:11], v[140:143], v[202:205], v[8:11]
	v_mfma_f32_16x16x32_bf16 v[52:55], v[144:147], v[160:163], v[52:55]
	v_mfma_f32_16x16x32_bf16 v[48:51], v[152:155], v[160:163], v[48:51]
	v_mfma_f32_16x16x32_bf16 v[36:39], v[144:147], v[168:171], v[36:39]
	v_mfma_f32_16x16x32_bf16 v[32:35], v[152:155], v[168:171], v[32:35]
	v_mfma_f32_16x16x32_bf16 v[20:23], v[144:147], v[182:185], v[20:23]
	v_mfma_f32_16x16x32_bf16 v[16:19], v[152:155], v[182:185], v[16:19]
	v_mfma_f32_16x16x32_bf16 v[4:7], v[144:147], v[198:201], v[4:7]
	v_mfma_f32_16x16x32_bf16 v[0:3], v[152:155], v[198:201], v[0:3]
	v_mfma_f32_16x16x32_bf16 v[52:55], v[148:151], v[164:167], v[52:55]
	v_mfma_f32_16x16x32_bf16 v[48:51], v[156:159], v[164:167], v[48:51]
	v_mfma_f32_16x16x32_bf16 v[36:39], v[148:151], v[178:181], v[36:39]
	v_mfma_f32_16x16x32_bf16 v[32:35], v[156:159], v[178:181], v[32:35]
	v_mfma_f32_16x16x32_bf16 v[20:23], v[148:151], v[186:189], v[20:23]
	v_mfma_f32_16x16x32_bf16 v[16:19], v[156:159], v[186:189], v[16:19]
	v_mfma_f32_16x16x32_bf16 v[4:7], v[148:151], v[202:205], v[4:7]
	v_mfma_f32_16x16x32_bf16 v[0:3], v[156:159], v[202:205], v[0:3]
	s_barrier
; #define PG8_STAGE(bufoff, gbase, voff) do { _Pragma("unroll") for (int _i = 0; _i < 2; ++_i) { unsigned _vo = (voff)[_i]; asm volatile("" : "+v"(_vo));   \
;         __builtin_amdgcn_global_load_lds((const unsigned*)((const char*)(gbase) + _vo), (LAS unsigned*)(lds + (bufoff) + ldsw + _i * 8192), 16, 0, 0); } } while (0)
; #define PG8_LDA(dst, b, h) do { _Pragma("unroll") for (int m = 0; m < 4; ++m) _Pragma("unroll") for (int k = 0; k < 2; ++k) dst[m][k] = *(const LAS bf16x8*)(lds + PG8_SA(b, h) + aoff + m * 2048 + k * 1024); } while (0)
; #define PG8_LDB(dst, b, h) do { _Pragma("unroll") for (int n = 0; n < 2; ++n) _Pragma("unroll") for (int k = 0; k < 2; ++k) dst[n][k] = *(const LAS bf16x8*)(lds + PG8_SB(b, h) + boff + n * 2048 + k * 1024); } while (0)
; #define PG8_WAIT_V(n) asm volatile("s_waitcnt vmcnt(" #n ")" ::: "memory")
; #define PG8_WAIT_L(n) asm volatile("s_waitcnt lgkmcnt(" #n ")" ::: "memory")
; #define PG8_BAR __builtin_amdgcn_s_barrier()
; #define PG8_SCHED __builtin_amdgcn_sched_barrier(0)
; template <bool F8 = false>
; __device__ __forceinline__ void gemm_phase(LAS unsigned char* lds, const int K, const Sched& S, const Epi& E, const int wave_s) {
;     ...
;             PG8_LDB(B0, 1, 0); PG8_LDB(B1, 1, 1); PG8_SCHED; PG8_LDA(At, 1, 0); PG8_STAGE(PG8_SA(0, 1), a2 + hstepA, voffA);
;             PG8_WAIT_V(8); PG8_WAIT_L(0); PG8_BAR; PG8_MMA(0, 0, At, B0); PG8_MMA(0, 1, At, B1); PG8_BAR; PG8_SCHED;
	s_add_i32 s79, 0, 0x18000
	s_add_i32 s80, 0, 0x1c000
	v_add_u32_e32 v140, s79, v194
	v_add_u32_e32 v156, s80, v194
	ds_read_b128 v[112:115], v140
	ds_read_b128 v[128:131], v140 offset:1024
	ds_read_b128 v[136:139], v140 offset:2048
	ds_read_b128 v[140:143], v140 offset:3072
	ds_read_b128 v[144:147], v156
	ds_read_b128 v[148:151], v156 offset:1024
	ds_read_b128 v[152:155], v156 offset:2048
	ds_read_b128 v[156:159], v156 offset:3072
	s_add_u32 s68, s38, 0x40000
	v_mov_b32_e32 v172, v190
	s_mov_b32 m0, s43
	ds_read_b128 v[160:163], v197 offset:32768
	ds_read_b128 v[164:167], v197 offset:33792
	ds_read_b128 v[168:171], v197 offset:34816
	ds_read_b128 v[178:181], v197 offset:35840
	ds_read_b128 v[182:185], v197 offset:36864
	ds_read_b128 v[186:189], v197 offset:37888
	ds_read_b128 v[198:201], v197 offset:38912
	ds_read_b128 v[202:205], v197 offset:39936
	s_addc_u32 s69, s39, 0
	s_nop 0
	global_load_lds_dwordx4 v172, s[68:69]
	v_mov_b32_e32 v172, v192
	s_mov_b32 m0, s44
	s_nop 0
	global_load_lds_dwordx4 v172, s[68:69]
	s_waitcnt vmcnt(8)
	s_waitcnt lgkmcnt(0)
	s_barrier
	s_waitcnt lgkmcnt(0)
	v_mfma_f32_16x16x32_bf16 v[104:107], v[112:115], v[160:163], v[104:107]
	v_mfma_f32_16x16x32_bf16 v[132:135], v[136:139], v[160:163], v[132:135]
	v_mfma_f32_16x16x32_bf16 v[116:119], v[112:115], v[168:171], v[116:119]
	v_mfma_f32_16x16x32_bf16 v[108:111], v[136:139], v[168:171], v[108:111]
	v_mfma_f32_16x16x32_bf16 v[92:95], v[112:115], v[182:185], v[92:95]
	v_mfma_f32_16x16x32_bf16 v[88:91], v[136:139], v[182:185], v[88:91]
	v_mfma_f32_16x16x32_bf16 v[76:79], v[112:115], v[198:201], v[76:79]
	v_mfma_f32_16x16x32_bf16 v[72:75], v[136:139], v[198:201], v[72:75]
	v_mfma_f32_16x16x32_bf16 v[104:107], v[128:131], v[164:167], v[104:107]
	v_mfma_f32_16x16x32_bf16 v[132:135], v[140:143], v[164:167], v[132:135]
	v_mfma_f32_16x16x32_bf16 v[116:119], v[128:131], v[178:181], v[116:119]
	v_mfma_f32_16x16x32_bf16 v[108:111], v[140:143], v[178:181], v[108:111]
	v_mfma_f32_16x16x32_bf16 v[92:95], v[128:131], v[186:189], v[92:95]
	v_mfma_f32_16x16x32_bf16 v[88:91], v[140:143], v[186:189], v[88:91]
	v_mfma_f32_16x16x32_bf16 v[76:79], v[128:131], v[202:205], v[76:79]
	v_mfma_f32_16x16x32_bf16 v[72:75], v[140:143], v[202:205], v[72:75]
	v_mfma_f32_16x16x32_bf16 v[124:127], v[144:147], v[160:163], v[124:127]
	v_mfma_f32_16x16x32_bf16 v[120:123], v[152:155], v[160:163], v[120:123]
	v_mfma_f32_16x16x32_bf16 v[100:103], v[144:147], v[168:171], v[100:103]
	v_mfma_f32_16x16x32_bf16 v[96:99], v[152:155], v[168:171], v[96:99]
	v_mfma_f32_16x16x32_bf16 v[84:87], v[144:147], v[182:185], v[84:87]
	v_mfma_f32_16x16x32_bf16 v[80:83], v[152:155], v[182:185], v[80:83]
	v_mfma_f32_16x16x32_bf16 v[68:71], v[144:147], v[198:201], v[68:71]
	v_mfma_f32_16x16x32_bf16 v[64:67], v[152:155], v[198:201], v[64:67]
	v_mfma_f32_16x16x32_bf16 v[124:127], v[148:151], v[164:167], v[124:127]
	v_mfma_f32_16x16x32_bf16 v[120:123], v[156:159], v[164:167], v[120:123]
	v_mfma_f32_16x16x32_bf16 v[100:103], v[148:151], v[178:181], v[100:103]
	v_mfma_f32_16x16x32_bf16 v[96:99], v[156:159], v[178:181], v[96:99]
	v_mfma_f32_16x16x32_bf16 v[84:87], v[148:151], v[186:189], v[84:87]
	v_mfma_f32_16x16x32_bf16 v[80:83], v[156:159], v[186:189], v[80:83]
	v_mfma_f32_16x16x32_bf16 v[68:71], v[148:151], v[202:205], v[68:71]
	v_mfma_f32_16x16x32_bf16 v[64:67], v[156:159], v[202:205], v[64:67]
	s_barrier
; #define PG8_STAGE(bufoff, gbase, voff) do { _Pragma("unroll") for (int _i = 0; _i < 2; ++_i) { unsigned _vo = (voff)[_i]; asm volatile("" : "+v"(_vo));   \
;         __builtin_amdgcn_global_load_lds((const unsigned*)((const char*)(gbase) + _vo), (LAS unsigned*)(lds + (bufoff) + ldsw + _i * 8192), 16, 0, 0); } } while (0)
; #define PG8_LDA(dst, b, h) do { _Pragma("unroll") for (int m = 0; m < 4; ++m) _Pragma("unroll") for (int k = 0; k < 2; ++k) dst[m][k] = *(const LAS bf16x8*)(lds + PG8_SA(b, h) + aoff + m * 2048 + k * 1024); } while (0)
; #define PG8_WAIT_V(n) asm volatile("s_waitcnt vmcnt(" #n ")" ::: "memory")
; #define PG8_WAIT_L(n) asm volatile("s_waitcnt lgkmcnt(" #n ")" ::: "memory")
; #define PG8_BAR __builtin_amdgcn_s_barrier()
; #define PG8_SCHED __builtin_amdgcn_sched_barrier(0)
; template <bool F8 = false>
; __device__ __forceinline__ void gemm_phase(LAS unsigned char* lds, const int K, const Sched& S, const Epi& E, const int wave_s) {
;     ...
;             PG8_LDA(At, 1, 1); PG8_STAGE(PG8_SB(1, 0), b3, voffB); PG8_STAGE(PG8_SB(1, 1), b3 + hstepB, voffB); PG8_STAGE(PG8_SA(1, 0), a3, voffA);
;             PG8_WAIT_V(8); PG8_WAIT_L(0); PG8_BAR; PG8_MMA(1, 0, At, B0); PG8_MMA(1, 1, At, B1); PG8_BAR; PG8_SCHED;
;         }
;         if (align) { if (wr == 0) PG8_BAR; }
	v_mov_b32_e32 v172, v191
	ds_read_b128 v[160:163], v197 offset:49152
	ds_read_b128 v[164:167], v197 offset:50176
	ds_read_b128 v[168:171], v197 offset:51200
	ds_read_b128 v[178:181], v197 offset:52224
	ds_read_b128 v[182:185], v197 offset:53248
	ds_read_b128 v[186:189], v197 offset:54272
	ds_read_b128 v[198:201], v197 offset:55296
	ds_read_b128 v[202:205], v197 offset:56320
	s_add_i32 s68, s79, s73
	v_lshl_add_u64 v[206:207], s[40:41], 0, v[172:173]
	v_lshl_add_u64 v[206:207], v[206:207], 0, s[8:9]
	s_mov_b32 m0, s68
	v_mov_b32_e32 v172, v193
	global_load_lds_dwordx4 v[206:207], off
	s_add_i32 m0, s68, 0x2000
	s_nop 0
	v_lshl_add_u64 v[206:207], s[40:41], 0, v[172:173]
	s_add_u32 s40, s40, 0x40080
	v_lshl_add_u64 v[206:207], v[206:207], 0, s[8:9]
	s_addc_u32 s41, s41, 0
	v_mov_b32_e32 v172, v191
	s_add_i32 s68, s80, s73
	global_load_lds_dwordx4 v[206:207], off
	s_mov_b32 m0, s68
	s_nop 0
	global_load_lds_dwordx4 v172, s[40:41]
	v_mov_b32_e32 v172, v193
	s_add_i32 m0, s68, 0x2000
	s_nop 0
	global_load_lds_dwordx4 v172, s[40:41]
	v_mov_b32_e32 v172, v190
	s_mov_b32 m0, s46
	v_lshl_add_u64 v[206:207], s[38:39], 0, v[172:173]
	v_lshl_add_u64 v[206:207], v[206:207], 0, s[8:9]
	v_mov_b32_e32 v172, v192
	global_load_lds_dwordx4 v[206:207], off
	s_mov_b32 m0, s47
	v_lshl_add_u64 v[206:207], s[38:39], 0, v[172:173]
	v_lshl_add_u64 v[206:207], v[206:207], 0, s[8:9]
	global_load_lds_dwordx4 v[206:207], off
	s_waitcnt vmcnt(8)
	s_waitcnt lgkmcnt(0)
	s_barrier
	s_waitcnt lgkmcnt(0)
	v_mfma_f32_16x16x32_bf16 v[60:63], v[112:115], v[160:163], v[60:63]
	v_mfma_f32_16x16x32_bf16 v[56:59], v[136:139], v[160:163], v[56:59]
	v_mfma_f32_16x16x32_bf16 v[44:47], v[112:115], v[168:171], v[44:47]
	v_mfma_f32_16x16x32_bf16 v[40:43], v[136:139], v[168:171], v[40:43]
	v_mfma_f32_16x16x32_bf16 v[28:31], v[112:115], v[182:185], v[28:31]
	v_mfma_f32_16x16x32_bf16 v[24:27], v[136:139], v[182:185], v[24:27]
	v_mfma_f32_16x16x32_bf16 v[12:15], v[112:115], v[198:201], v[12:15]
	v_mfma_f32_16x16x32_bf16 v[8:11], v[136:139], v[198:201], v[8:11]
	v_mfma_f32_16x16x32_bf16 v[60:63], v[128:131], v[164:167], v[60:63]
	v_mfma_f32_16x16x32_bf16 v[56:59], v[140:143], v[164:167], v[56:59]
	v_mfma_f32_16x16x32_bf16 v[44:47], v[128:131], v[178:181], v[44:47]
	v_mfma_f32_16x16x32_bf16 v[40:43], v[140:143], v[178:181], v[40:43]
	v_mfma_f32_16x16x32_bf16 v[28:31], v[128:131], v[186:189], v[28:31]
	v_mfma_f32_16x16x32_bf16 v[24:27], v[140:143], v[186:189], v[24:27]
	v_mfma_f32_16x16x32_bf16 v[12:15], v[128:131], v[202:205], v[12:15]
	v_mfma_f32_16x16x32_bf16 v[8:11], v[140:143], v[202:205], v[8:11]
	v_mfma_f32_16x16x32_bf16 v[52:55], v[144:147], v[160:163], v[52:55]
	v_mfma_f32_16x16x32_bf16 v[48:51], v[152:155], v[160:163], v[48:51]
	v_mfma_f32_16x16x32_bf16 v[36:39], v[144:147], v[168:171], v[36:39]
	v_mfma_f32_16x16x32_bf16 v[32:35], v[152:155], v[168:171], v[32:35]
	v_mfma_f32_16x16x32_bf16 v[20:23], v[144:147], v[182:185], v[20:23]
	v_mfma_f32_16x16x32_bf16 v[16:19], v[152:155], v[182:185], v[16:19]
	v_mfma_f32_16x16x32_bf16 v[4:7], v[144:147], v[198:201], v[4:7]
	v_mfma_f32_16x16x32_bf16 v[0:3], v[152:155], v[198:201], v[0:3]
	v_mfma_f32_16x16x32_bf16 v[52:55], v[148:151], v[164:167], v[52:55]
	v_mfma_f32_16x16x32_bf16 v[48:51], v[156:159], v[164:167], v[48:51]
	v_mfma_f32_16x16x32_bf16 v[36:39], v[148:151], v[178:181], v[36:39]
	v_mfma_f32_16x16x32_bf16 v[32:35], v[156:159], v[178:181], v[32:35]
	v_mfma_f32_16x16x32_bf16 v[20:23], v[148:151], v[186:189], v[20:23]
	v_mfma_f32_16x16x32_bf16 v[16:19], v[156:159], v[186:189], v[16:19]
	v_mfma_f32_16x16x32_bf16 v[4:7], v[148:151], v[202:205], v[4:7]
	v_mfma_f32_16x16x32_bf16 v[0:3], v[156:159], v[202:205], v[0:3]
	s_barrier
	s_add_i32 s63, s63, 2
	s_add_u32 s36, s36, 0x100
	s_addc_u32 s37, s37, 0
	s_add_u32 s13, s13, 0x100
	s_addc_u32 s62, s62, 0
	s_cmp_gt_u32 s63, 13
	s_cbranch_scc0 .LBB0_981
	s_setprio 0
	s_and_b64 vcc, exec, s[10:11]
	s_cbranch_vccz .LBB0_984
	s_barrier

; #define PG8_STAGE(bufoff, gbase, voff) do { _Pragma("unroll") for (int _i = 0; _i < 2; ++_i) { unsigned _vo = (voff)[_i]; asm volatile("" : "+v"(_vo));   \
;         __builtin_amdgcn_global_load_lds((const unsigned*)((const char*)(gbase) + _vo), (LAS unsigned*)(lds + (bufoff) + ldsw + _i * 8192), 16, 0, 0); } } while (0)
; #define PG8_LDA(dst, b, h) do { _Pragma("unroll") for (int m = 0; m < 4; ++m) _Pragma("unroll") for (int k = 0; k < 2; ++k) dst[m][k] = *(const LAS bf16x8*)(lds + PG8_SA(b, h) + aoff + m * 2048 + k * 1024); } while (0)
; #define PG8_LDB(dst, b, h) do { _Pragma("unroll") for (int n = 0; n < 2; ++n) _Pragma("unroll") for (int k = 0; k < 2; ++k) dst[n][k] = *(const LAS bf16x8*)(lds + PG8_SB(b, h) + boff + n * 2048 + k * 1024); } while (0)
; #define PG8_WAIT_V(n) asm volatile("s_waitcnt vmcnt(" #n ")" ::: "memory")
; #define PG8_WAIT_L(n) asm volatile("s_waitcnt lgkmcnt(" #n ")" ::: "memory")
; #define PG8_BAR __builtin_amdgcn_s_barrier()
; #define PG8_SCHED __builtin_amdgcn_sched_barrier(0)
; template <bool F8 = false>
; __device__ __forceinline__ void gemm_phase(LAS unsigned char* lds, const int K, const Sched& S, const Epi& E, const int wave_s) {
;     ...
;             PG8_LDB(B0, 0, 0); PG8_LDB(B1, 0, 1); PG8_SCHED; PG8_LDA(At, 0, 0); PG8_STAGE(PG8_SA(1, 1), a1 + hstepA, voffA);
;             PG8_WAIT_V(8); PG8_WAIT_L(0); PG8_BAR; PG8_MMA(0, 0, At, B0); PG8_MMA(0, 1, At, B1); PG8_BAR; PG8_SCHED;
;             PG8_LDA(At, 0, 1); PG8_STAGE(PG8_SB(0, 0), b2, voffB); PG8_STAGE(PG8_SB(0, 1), b2 + hstepB, voffB); PG8_STAGE(PG8_SA(0, 0), a2, voffA);
;             PG8_WAIT_V(8); PG8_WAIT_L(0); PG8_BAR; PG8_MMA(1, 0, At, B0); PG8_MMA(1, 1, At, B1); PG8_BAR; PG8_SCHED;
.Lmy_prio4:
	v_add_u32_e32 v0, s79, v220
	ds_read_b128 v[132:135], v0
	ds_read_b128 v[136:139], v0 offset:1024
	ds_read_b128 v[140:143], v0 offset:2048
	ds_read_b128 v[144:147], v0 offset:3072
	v_add_u32_e32 v0, s80, v220
	ds_read_b128 v[148:151], v0
	ds_read_b128 v[152:155], v0 offset:1024
	ds_read_b128 v[156:159], v0 offset:2048
	ds_read_b128 v[160:163], v0 offset:3072
	s_add_u32 s42, s38, 0xfffc0080
	s_addc_u32 s43, s39, -1
	s_cmp_eq_u32 s84, 12
	s_cselect_b32 s43, s37, s43
	s_cselect_b32 s42, s36, s42
	s_cselect_b32 s45, s41, s63
	s_cselect_b32 s44, s40, s29
	v_mov_b32_e32 v0, v216
	ds_read_b128 v[164:167], v221
	ds_read_b128 v[168:171], v221 offset:1024
	ds_read_b128 v[172:175], v221 offset:2048
	ds_read_b128 v[176:179], v221 offset:3072
	ds_read_b128 v[180:183], v221 offset:4096
	ds_read_b128 v[184:187], v221 offset:5120
	ds_read_b128 v[188:191], v221 offset:6144
	ds_read_b128 v[192:195], v221 offset:7168
	s_add_i32 m0, s46, 0xc000
	s_nop 0
	global_load_lds_dwordx4 v0, s[38:39]
	v_mov_b32_e32 v0, v218
	s_add_i32 m0, s46, 0xe000
	s_nop 0
	global_load_lds_dwordx4 v0, s[38:39]
	s_waitcnt vmcnt(8)
	s_waitcnt lgkmcnt(0)
	s_barrier
	s_waitcnt lgkmcnt(0)
	v_mfma_f32_16x16x32_bf16 v[128:131], v[132:135], v[164:167], v[128:131]
	v_mfma_f32_16x16x32_bf16 v[124:127], v[140:143], v[164:167], v[124:127]
	v_mfma_f32_16x16x32_bf16 v[120:123], v[132:135], v[172:175], v[120:123]
	v_mfma_f32_16x16x32_bf16 v[116:119], v[140:143], v[172:175], v[116:119]
	v_mfma_f32_16x16x32_bf16 v[112:115], v[132:135], v[180:183], v[112:115]
	v_mfma_f32_16x16x32_bf16 v[108:111], v[140:143], v[180:183], v[108:111]
	v_mfma_f32_16x16x32_bf16 v[104:107], v[132:135], v[188:191], v[104:107]
	v_mfma_f32_16x16x32_bf16 v[100:103], v[140:143], v[188:191], v[100:103]
	v_mfma_f32_16x16x32_bf16 v[128:131], v[136:139], v[168:171], v[128:131]
	v_mfma_f32_16x16x32_bf16 v[124:127], v[144:147], v[168:171], v[124:127]
	v_mfma_f32_16x16x32_bf16 v[120:123], v[136:139], v[176:179], v[120:123]
	v_mfma_f32_16x16x32_bf16 v[116:119], v[144:147], v[176:179], v[116:119]
	v_mfma_f32_16x16x32_bf16 v[112:115], v[136:139], v[184:187], v[112:115]
	v_mfma_f32_16x16x32_bf16 v[108:111], v[144:147], v[184:187], v[108:111]
	v_mfma_f32_16x16x32_bf16 v[104:107], v[136:139], v[192:195], v[104:107]
	v_mfma_f32_16x16x32_bf16 v[100:103], v[144:147], v[192:195], v[100:103]
	v_mfma_f32_16x16x32_bf16 v[96:99], v[148:151], v[164:167], v[96:99]
	v_mfma_f32_16x16x32_bf16 v[88:91], v[156:159], v[164:167], v[88:91]
	v_mfma_f32_16x16x32_bf16 v[80:83], v[148:151], v[172:175], v[80:83]
	v_mfma_f32_16x16x32_bf16 v[72:75], v[156:159], v[172:175], v[72:75]
	v_mfma_f32_16x16x32_bf16 v[64:67], v[148:151], v[180:183], v[64:67]
	v_mfma_f32_16x16x32_bf16 v[56:59], v[156:159], v[180:183], v[56:59]
	v_mfma_f32_16x16x32_bf16 v[48:51], v[148:151], v[188:191], v[48:51]
	v_mfma_f32_16x16x32_bf16 v[40:43], v[156:159], v[188:191], v[40:43]
	v_mfma_f32_16x16x32_bf16 v[96:99], v[152:155], v[168:171], v[96:99]
	v_mfma_f32_16x16x32_bf16 v[88:91], v[160:163], v[168:171], v[88:91]
	v_mfma_f32_16x16x32_bf16 v[80:83], v[152:155], v[176:179], v[80:83]
	v_mfma_f32_16x16x32_bf16 v[72:75], v[160:163], v[176:179], v[72:75]
	v_mfma_f32_16x16x32_bf16 v[64:67], v[152:155], v[184:187], v[64:67]
	v_mfma_f32_16x16x32_bf16 v[56:59], v[160:163], v[184:187], v[56:59]
	v_mfma_f32_16x16x32_bf16 v[48:51], v[152:155], v[192:195], v[48:51]
	v_mfma_f32_16x16x32_bf16 v[40:43], v[160:163], v[192:195], v[40:43]
	s_barrier
	v_mov_b32_e32 v0, v217
	s_add_i32 s85, s79, s73
	ds_read_b128 v[164:167], v221 offset:16384
	ds_read_b128 v[168:171], v221 offset:17408
	ds_read_b128 v[172:175], v221 offset:18432
	ds_read_b128 v[176:179], v221 offset:19456
	ds_read_b128 v[180:183], v221 offset:20480
	ds_read_b128 v[184:187], v221 offset:21504
	ds_read_b128 v[188:191], v221 offset:22528
	ds_read_b128 v[192:195], v221 offset:23552
	s_mov_b32 m0, s85
	s_nop 0
	global_load_lds_dwordx4 v0, s[44:45]
	v_mov_b32_e32 v0, v219
	s_add_i32 m0, s85, 0x2000
	s_add_u32 s86, s44, 0x40000
	global_load_lds_dwordx4 v0, s[44:45]
	s_addc_u32 s87, s45, 0
	v_mov_b32_e32 v0, v217
	s_add_i32 s85, s80, s73
	s_mov_b32 m0, s85
	s_nop 0
	global_load_lds_dwordx4 v0, s[86:87]
	v_mov_b32_e32 v0, v219
	s_add_i32 m0, s85, 0x2000
	s_nop 0
	global_load_lds_dwordx4 v0, s[86:87]
	v_mov_b32_e32 v0, v216
	s_mov_b32 m0, s46
	s_nop 0
	global_load_lds_dwordx4 v0, s[42:43]
	v_mov_b32_e32 v0, v218
	s_mov_b32 m0, s47
	s_nop 0
	global_load_lds_dwordx4 v0, s[42:43]
	s_waitcnt vmcnt(8)
	s_waitcnt lgkmcnt(0)
	s_barrier
	s_waitcnt lgkmcnt(0)
	v_mfma_f32_16x16x32_bf16 v[92:95], v[132:135], v[164:167], v[92:95]
	v_mfma_f32_16x16x32_bf16 v[84:87], v[140:143], v[164:167], v[84:87]
	v_mfma_f32_16x16x32_bf16 v[76:79], v[132:135], v[172:175], v[76:79]
	v_mfma_f32_16x16x32_bf16 v[68:71], v[140:143], v[172:175], v[68:71]
	v_mfma_f32_16x16x32_bf16 v[60:63], v[132:135], v[180:183], v[60:63]
	v_mfma_f32_16x16x32_bf16 v[52:55], v[140:143], v[180:183], v[52:55]
	v_mfma_f32_16x16x32_bf16 v[44:47], v[132:135], v[188:191], v[44:47]
	v_mfma_f32_16x16x32_bf16 v[36:39], v[140:143], v[188:191], v[36:39]
	v_mfma_f32_16x16x32_bf16 v[92:95], v[136:139], v[168:171], v[92:95]
	v_mfma_f32_16x16x32_bf16 v[84:87], v[144:147], v[168:171], v[84:87]
	v_mfma_f32_16x16x32_bf16 v[76:79], v[136:139], v[176:179], v[76:79]
	v_mfma_f32_16x16x32_bf16 v[68:71], v[144:147], v[176:179], v[68:71]
	v_mfma_f32_16x16x32_bf16 v[60:63], v[136:139], v[184:187], v[60:63]
	v_mfma_f32_16x16x32_bf16 v[52:55], v[144:147], v[184:187], v[52:55]
	v_mfma_f32_16x16x32_bf16 v[44:47], v[136:139], v[192:195], v[44:47]
	v_mfma_f32_16x16x32_bf16 v[36:39], v[144:147], v[192:195], v[36:39]
	v_mfma_f32_16x16x32_bf16 v[32:35], v[148:151], v[164:167], v[32:35]
	v_mfma_f32_16x16x32_bf16 v[28:31], v[156:159], v[164:167], v[28:31]
	v_mfma_f32_16x16x32_bf16 v[24:27], v[148:151], v[172:175], v[24:27]
	v_mfma_f32_16x16x32_bf16 v[20:23], v[156:159], v[172:175], v[20:23]
	v_mfma_f32_16x16x32_bf16 v[16:19], v[148:151], v[180:183], v[16:19]
	v_mfma_f32_16x16x32_bf16 v[12:15], v[156:159], v[180:183], v[12:15]
	v_mfma_f32_16x16x32_bf16 v[8:11], v[148:151], v[188:191], v[8:11]
	v_mfma_f32_16x16x32_bf16 v[2:5], v[156:159], v[188:191], v[4:7]
	v_mfma_f32_16x16x32_bf16 v[32:35], v[152:155], v[168:171], v[32:35]
	v_mfma_f32_16x16x32_bf16 v[28:31], v[160:163], v[168:171], v[28:31]
	v_mfma_f32_16x16x32_bf16 v[24:27], v[152:155], v[176:179], v[24:27]
	v_mfma_f32_16x16x32_bf16 v[20:23], v[160:163], v[176:179], v[20:23]
	v_mfma_f32_16x16x32_bf16 v[16:19], v[152:155], v[184:187], v[16:19]
	v_mfma_f32_16x16x32_bf16 v[12:15], v[160:163], v[184:187], v[12:15]
	v_mfma_f32_16x16x32_bf16 v[8:11], v[152:155], v[192:195], v[8:11]
	v_mfma_f32_16x16x32_bf16 v[2:5], v[160:163], v[192:195], v[2:5]
	s_barrier
; #define PG8_STAGE(bufoff, gbase, voff) do { _Pragma("unroll") for (int _i = 0; _i < 2; ++_i) { unsigned _vo = (voff)[_i]; asm volatile("" : "+v"(_vo));   \
;         __builtin_amdgcn_global_load_lds((const unsigned*)((const char*)(gbase) + _vo), (LAS unsigned*)(lds + (bufoff) + ldsw + _i * 8192), 16, 0, 0); } } while (0)
; #define PG8_LDA(dst, b, h) do { _Pragma("unroll") for (int m = 0; m < 4; ++m) _Pragma("unroll") for (int k = 0; k < 2; ++k) dst[m][k] = *(const LAS bf16x8*)(lds + PG8_SA(b, h) + aoff + m * 2048 + k * 1024); } while (0)
; #define PG8_LDB(dst, b, h) do { _Pragma("unroll") for (int n = 0; n < 2; ++n) _Pragma("unroll") for (int k = 0; k < 2; ++k) dst[n][k] = *(const LAS bf16x8*)(lds + PG8_SB(b, h) + boff + n * 2048 + k * 1024); } while (0)
; #define PG8_WAIT_V(n) asm volatile("s_waitcnt vmcnt(" #n ")" ::: "memory")
; #define PG8_WAIT_L(n) asm volatile("s_waitcnt lgkmcnt(" #n ")" ::: "memory")
; #define PG8_BAR __builtin_amdgcn_s_barrier()
; #define PG8_SCHED __builtin_amdgcn_sched_barrier(0)
; template <bool F8 = false>
; __device__ __forceinline__ void gemm_phase(LAS unsigned char* lds, const int K, const Sched& S, const Epi& E, const int wave_s) {
;     ...
;             PG8_LDB(B0, 1, 0); PG8_LDB(B1, 1, 1); PG8_SCHED; PG8_LDA(At, 1, 0); PG8_STAGE(PG8_SA(0, 1), a2 + hstepA, voffA);
;             PG8_WAIT_V(8); PG8_WAIT_L(0); PG8_BAR; PG8_MMA(0, 0, At, B0); PG8_MMA(0, 1, At, B1); PG8_BAR; PG8_SCHED;
	s_add_i32 s85, 0, 0x18000
	v_add_u32_e32 v0, s85, v220
	s_add_i32 s88, 0, 0x1c000
	ds_read_b128 v[132:135], v0
	ds_read_b128 v[136:139], v0 offset:1024
	ds_read_b128 v[140:143], v0 offset:2048
	ds_read_b128 v[144:147], v0 offset:3072
	v_add_u32_e32 v0, s88, v220
	ds_read_b128 v[148:151], v0
	ds_read_b128 v[152:155], v0 offset:1024
	ds_read_b128 v[156:159], v0 offset:2048
	ds_read_b128 v[160:163], v0 offset:3072
	s_add_u32 s86, s42, 0x40000
	v_mov_b32_e32 v0, v216
	s_mov_b32 m0, s48
	ds_read_b128 v[164:167], v221 offset:32768
	ds_read_b128 v[168:171], v221 offset:33792
	ds_read_b128 v[172:175], v221 offset:34816
	ds_read_b128 v[176:179], v221 offset:35840
	ds_read_b128 v[180:183], v221 offset:36864
	ds_read_b128 v[184:187], v221 offset:37888
	ds_read_b128 v[188:191], v221 offset:38912
	ds_read_b128 v[192:195], v221 offset:39936
	s_addc_u32 s87, s43, 0
	s_nop 0
	global_load_lds_dwordx4 v0, s[86:87]
	v_mov_b32_e32 v0, v218
	s_mov_b32 m0, s49
	s_nop 0
	global_load_lds_dwordx4 v0, s[86:87]
	s_waitcnt vmcnt(8)
	s_waitcnt lgkmcnt(0)
	s_barrier
	s_waitcnt lgkmcnt(0)
	v_mfma_f32_16x16x32_bf16 v[128:131], v[132:135], v[164:167], v[128:131]
	v_mfma_f32_16x16x32_bf16 v[124:127], v[140:143], v[164:167], v[124:127]
	v_mfma_f32_16x16x32_bf16 v[120:123], v[132:135], v[172:175], v[120:123]
	v_mfma_f32_16x16x32_bf16 v[116:119], v[140:143], v[172:175], v[116:119]
	v_mfma_f32_16x16x32_bf16 v[112:115], v[132:135], v[180:183], v[112:115]
	v_mfma_f32_16x16x32_bf16 v[108:111], v[140:143], v[180:183], v[108:111]
	v_mfma_f32_16x16x32_bf16 v[104:107], v[132:135], v[188:191], v[104:107]
	v_mfma_f32_16x16x32_bf16 v[100:103], v[140:143], v[188:191], v[100:103]
	v_mfma_f32_16x16x32_bf16 v[128:131], v[136:139], v[168:171], v[128:131]
	v_mfma_f32_16x16x32_bf16 v[124:127], v[144:147], v[168:171], v[124:127]
	v_mfma_f32_16x16x32_bf16 v[120:123], v[136:139], v[176:179], v[120:123]
	v_mfma_f32_16x16x32_bf16 v[116:119], v[144:147], v[176:179], v[116:119]
	v_mfma_f32_16x16x32_bf16 v[112:115], v[136:139], v[184:187], v[112:115]
	v_mfma_f32_16x16x32_bf16 v[108:111], v[144:147], v[184:187], v[108:111]
	v_mfma_f32_16x16x32_bf16 v[104:107], v[136:139], v[192:195], v[104:107]
	v_mfma_f32_16x16x32_bf16 v[100:103], v[144:147], v[192:195], v[100:103]
	v_mfma_f32_16x16x32_bf16 v[96:99], v[148:151], v[164:167], v[96:99]
	v_mfma_f32_16x16x32_bf16 v[88:91], v[156:159], v[164:167], v[88:91]
	v_mfma_f32_16x16x32_bf16 v[80:83], v[148:151], v[172:175], v[80:83]
	v_mfma_f32_16x16x32_bf16 v[72:75], v[156:159], v[172:175], v[72:75]
	v_mfma_f32_16x16x32_bf16 v[64:67], v[148:151], v[180:183], v[64:67]
	v_mfma_f32_16x16x32_bf16 v[56:59], v[156:159], v[180:183], v[56:59]
	v_mfma_f32_16x16x32_bf16 v[48:51], v[148:151], v[188:191], v[48:51]
	v_mfma_f32_16x16x32_bf16 v[40:43], v[156:159], v[188:191], v[40:43]
	v_mfma_f32_16x16x32_bf16 v[96:99], v[152:155], v[168:171], v[96:99]
	v_mfma_f32_16x16x32_bf16 v[88:91], v[160:163], v[168:171], v[88:91]
	v_mfma_f32_16x16x32_bf16 v[80:83], v[152:155], v[176:179], v[80:83]
	v_mfma_f32_16x16x32_bf16 v[72:75], v[160:163], v[176:179], v[72:75]
	v_mfma_f32_16x16x32_bf16 v[64:67], v[152:155], v[184:187], v[64:67]
	v_mfma_f32_16x16x32_bf16 v[56:59], v[160:163], v[184:187], v[56:59]
	v_mfma_f32_16x16x32_bf16 v[48:51], v[152:155], v[192:195], v[48:51]
	v_mfma_f32_16x16x32_bf16 v[40:43], v[160:163], v[192:195], v[40:43]
	s_barrier
; #define PG8_STAGE(bufoff, gbase, voff) do { _Pragma("unroll") for (int _i = 0; _i < 2; ++_i) { unsigned _vo = (voff)[_i]; asm volatile("" : "+v"(_vo));   \
;         __builtin_amdgcn_global_load_lds((const unsigned*)((const char*)(gbase) + _vo), (LAS unsigned*)(lds + (bufoff) + ldsw + _i * 8192), 16, 0, 0); } } while (0)
; #define PG8_LDA(dst, b, h) do { _Pragma("unroll") for (int m = 0; m < 4; ++m) _Pragma("unroll") for (int k = 0; k < 2; ++k) dst[m][k] = *(const LAS bf16x8*)(lds + PG8_SA(b, h) + aoff + m * 2048 + k * 1024); } while (0)
; #define PG8_WAIT_V(n) asm volatile("s_waitcnt vmcnt(" #n ")" ::: "memory")
; #define PG8_WAIT_L(n) asm volatile("s_waitcnt lgkmcnt(" #n ")" ::: "memory")
; #define PG8_BAR __builtin_amdgcn_s_barrier()
; #define PG8_SCHED __builtin_amdgcn_sched_barrier(0)
; template <bool F8 = false>
; __device__ __forceinline__ void gemm_phase(LAS unsigned char* lds, const int K, const Sched& S, const Epi& E, const int wave_s) {
;     ...
;             PG8_LDA(At, 1, 1); PG8_STAGE(PG8_SB(1, 0), b3, voffB); PG8_STAGE(PG8_SB(1, 1), b3 + hstepB, voffB); PG8_STAGE(PG8_SA(1, 0), a3, voffA);
;             PG8_WAIT_V(8); PG8_WAIT_L(0); PG8_BAR; PG8_MMA(1, 0, At, B0); PG8_MMA(1, 1, At, B1); PG8_BAR; PG8_SCHED;
;         }
;         if (align) { if (wr == 0) PG8_BAR; }
	v_mov_b32_e32 v0, v217
	ds_read_b128 v[164:167], v221 offset:49152
	ds_read_b128 v[168:171], v221 offset:50176
	ds_read_b128 v[172:175], v221 offset:51200
	ds_read_b128 v[176:179], v221 offset:52224
	ds_read_b128 v[180:183], v221 offset:53248
	ds_read_b128 v[184:187], v221 offset:54272
	ds_read_b128 v[188:191], v221 offset:55296
	ds_read_b128 v[192:195], v221 offset:56320
	s_add_i32 s85, s85, s73
	v_lshl_add_u64 v[6:7], s[44:45], 0, v[0:1]
	v_lshl_add_u64 v[6:7], v[6:7], 0, s[16:17]
	s_mov_b32 m0, s85
	v_mov_b32_e32 v0, v219
	global_load_lds_dwordx4 v[6:7], off
	s_add_i32 m0, s85, 0x2000
	s_nop 0
	v_lshl_add_u64 v[6:7], s[44:45], 0, v[0:1]
	s_add_u32 s44, s44, 0x40080
	v_lshl_add_u64 v[6:7], v[6:7], 0, s[16:17]
	s_addc_u32 s45, s45, 0
	v_mov_b32_e32 v0, v217
	s_add_i32 s85, s88, s73
	global_load_lds_dwordx4 v[6:7], off
	s_mov_b32 m0, s85
	s_nop 0
	global_load_lds_dwordx4 v0, s[44:45]
	v_mov_b32_e32 v0, v219
	s_add_i32 m0, s85, 0x2000
	s_nop 0
	global_load_lds_dwordx4 v0, s[44:45]
	v_mov_b32_e32 v0, v216
	s_mov_b32 m0, s68
	v_lshl_add_u64 v[6:7], s[42:43], 0, v[0:1]
	v_lshl_add_u64 v[6:7], v[6:7], 0, s[16:17]
	v_mov_b32_e32 v0, v218
	global_load_lds_dwordx4 v[6:7], off
	s_mov_b32 m0, s69
	v_lshl_add_u64 v[6:7], s[42:43], 0, v[0:1]
	v_lshl_add_u64 v[6:7], v[6:7], 0, s[16:17]
	global_load_lds_dwordx4 v[6:7], off
	s_waitcnt vmcnt(8)
	s_waitcnt lgkmcnt(0)
	s_barrier
	s_waitcnt lgkmcnt(0)
	v_mfma_f32_16x16x32_bf16 v[92:95], v[132:135], v[164:167], v[92:95]
	v_mfma_f32_16x16x32_bf16 v[84:87], v[140:143], v[164:167], v[84:87]
	v_mfma_f32_16x16x32_bf16 v[76:79], v[132:135], v[172:175], v[76:79]
	v_mfma_f32_16x16x32_bf16 v[68:71], v[140:143], v[172:175], v[68:71]
	v_mfma_f32_16x16x32_bf16 v[60:63], v[132:135], v[180:183], v[60:63]
	v_mfma_f32_16x16x32_bf16 v[52:55], v[140:143], v[180:183], v[52:55]
	v_mfma_f32_16x16x32_bf16 v[44:47], v[132:135], v[188:191], v[44:47]
	v_mfma_f32_16x16x32_bf16 v[36:39], v[140:143], v[188:191], v[36:39]
	v_mfma_f32_16x16x32_bf16 v[92:95], v[136:139], v[168:171], v[92:95]
	v_mfma_f32_16x16x32_bf16 v[84:87], v[144:147], v[168:171], v[84:87]
	v_mfma_f32_16x16x32_bf16 v[76:79], v[136:139], v[176:179], v[76:79]
	v_mfma_f32_16x16x32_bf16 v[68:71], v[144:147], v[176:179], v[68:71]
	v_mfma_f32_16x16x32_bf16 v[60:63], v[136:139], v[184:187], v[60:63]
	v_mfma_f32_16x16x32_bf16 v[52:55], v[144:147], v[184:187], v[52:55]
	v_mfma_f32_16x16x32_bf16 v[44:47], v[136:139], v[192:195], v[44:47]
	v_mfma_f32_16x16x32_bf16 v[36:39], v[144:147], v[192:195], v[36:39]
	v_mfma_f32_16x16x32_bf16 v[32:35], v[148:151], v[164:167], v[32:35]
	v_mfma_f32_16x16x32_bf16 v[28:31], v[156:159], v[164:167], v[28:31]
	v_mfma_f32_16x16x32_bf16 v[24:27], v[148:151], v[172:175], v[24:27]
	v_mfma_f32_16x16x32_bf16 v[20:23], v[156:159], v[172:175], v[20:23]
	v_mfma_f32_16x16x32_bf16 v[16:19], v[148:151], v[180:183], v[16:19]
	v_mfma_f32_16x16x32_bf16 v[12:15], v[156:159], v[180:183], v[12:15]
	v_mfma_f32_16x16x32_bf16 v[6:9], v[148:151], v[188:191], v[8:11]
	v_mfma_f32_16x16x32_bf16 v[2:5], v[156:159], v[188:191], v[2:5]
	v_mfma_f32_16x16x32_bf16 v[32:35], v[152:155], v[168:171], v[32:35]
	v_mfma_f32_16x16x32_bf16 v[28:31], v[160:163], v[168:171], v[28:31]
	v_mfma_f32_16x16x32_bf16 v[24:27], v[152:155], v[176:179], v[24:27]
	v_mfma_f32_16x16x32_bf16 v[20:23], v[160:163], v[176:179], v[20:23]
	v_mfma_f32_16x16x32_bf16 v[16:19], v[152:155], v[184:187], v[16:19]
	v_mfma_f32_16x16x32_bf16 v[12:15], v[160:163], v[184:187], v[12:15]
	v_mfma_f32_16x16x32_bf16 v[8:11], v[152:155], v[192:195], v[6:9]
	v_mfma_f32_16x16x32_bf16 v[4:7], v[160:163], v[192:195], v[2:5]
	s_barrier
	s_add_i32 s84, s84, 2
	s_add_u32 s38, s38, 0x100
	s_addc_u32 s39, s39, 0
	s_add_u32 s29, s29, 0x100
	s_addc_u32 s63, s63, 0
	s_cmp_gt_u32 s84, 13
	s_cbranch_scc0 .LBB0_1061
	s_setprio 0
	s_and_b64 vcc, exec, s[18:19]
	s_cbranch_vccz .LBB0_1064
	s_barrier

; #define PG8_STAGE(bufoff, gbase, voff) do { _Pragma("unroll") for (int _i = 0; _i < 2; ++_i) { unsigned _vo = (voff)[_i]; asm volatile("" : "+v"(_vo));   \
;         __builtin_amdgcn_global_load_lds((const unsigned*)((const char*)(gbase) + _vo), (LAS unsigned*)(lds + (bufoff) + ldsw + _i * 8192), 16, 0, 0); } } while (0)
; #define PG8_LDA(dst, b, h) do { _Pragma("unroll") for (int m = 0; m < 4; ++m) _Pragma("unroll") for (int k = 0; k < 2; ++k) dst[m][k] = *(const LAS bf16x8*)(lds + PG8_SA(b, h) + aoff + m * 2048 + k * 1024); } while (0)
; #define PG8_LDB(dst, b, h) do { _Pragma("unroll") for (int n = 0; n < 2; ++n) _Pragma("unroll") for (int k = 0; k < 2; ++k) dst[n][k] = *(const LAS bf16x8*)(lds + PG8_SB(b, h) + boff + n * 2048 + k * 1024); } while (0)
; #define PG8_WAIT_V(n) asm volatile("s_waitcnt vmcnt(" #n ")" ::: "memory")
; #define PG8_WAIT_L(n) asm volatile("s_waitcnt lgkmcnt(" #n ")" ::: "memory")
; #define PG8_BAR __builtin_amdgcn_s_barrier()
; #define PG8_SCHED __builtin_amdgcn_sched_barrier(0)
; template <bool F8 = false>
; __device__ __forceinline__ void gemm_phase(LAS unsigned char* lds, const int K, const Sched& S, const Epi& E, const int wave_s) {
;     ...
;             PG8_LDB(B0, 0, 0); PG8_LDB(B1, 0, 1); PG8_SCHED; PG8_LDA(At, 0, 0); PG8_STAGE(PG8_SA(1, 1), a1 + hstepA, voffA);
;             PG8_WAIT_V(8); PG8_WAIT_L(0); PG8_BAR; PG8_MMA(0, 0, At, B0); PG8_MMA(0, 1, At, B1); PG8_BAR; PG8_SCHED;
;             PG8_LDA(At, 0, 1); PG8_STAGE(PG8_SB(0, 0), b2, voffB); PG8_STAGE(PG8_SB(0, 1), b2 + hstepB, voffB); PG8_STAGE(PG8_SA(0, 0), a2, voffA);
;             PG8_WAIT_V(8); PG8_WAIT_L(0); PG8_BAR; PG8_MMA(1, 0, At, B0); PG8_MMA(1, 1, At, B1); PG8_BAR; PG8_SCHED;
.Lmy_prio5:
	ds_read_b128 v[128:131], v161
	ds_read_b128 v[132:135], v161 offset:1024
	ds_read_b128 v[136:139], v161 offset:2048
	ds_read_b128 v[140:143], v161 offset:3072
	ds_read_b128 v[150:153], v162
	ds_read_b128 v[164:167], v162 offset:1024
	ds_read_b128 v[168:171], v162 offset:2048
	ds_read_b128 v[172:175], v162 offset:3072
	s_add_u32 s40, s38, 0xfff80080
	s_addc_u32 s41, s39, -1
	s_cmp_eq_u32 s69, 28
	s_cselect_b32 s41, s35, s41
	s_cselect_b32 s40, s34, s40
	s_cselect_b32 s43, s37, s63
	s_cselect_b32 s42, s36, s23
	v_mov_b32_e32 v144, v156
	ds_read_b128 v[176:179], v163
	ds_read_b128 v[180:183], v163 offset:1024
	ds_read_b128 v[184:187], v163 offset:2048
	ds_read_b128 v[188:191], v163 offset:3072
	ds_read_b128 v[192:195], v163 offset:4096
	ds_read_b128 v[196:199], v163 offset:5120
	ds_read_b128 v[200:203], v163 offset:6144
	ds_read_b128 v[204:207], v163 offset:7168
	s_add_i32 m0, s31, 0xc000
	s_nop 0
	global_load_lds_dwordx4 v144, s[38:39]
	v_mov_b32_e32 v144, v158
	s_add_i32 m0, s31, 0xe000
	s_nop 0
	global_load_lds_dwordx4 v144, s[38:39]
	s_waitcnt vmcnt(8)
	s_waitcnt lgkmcnt(0)
	s_barrier
	s_waitcnt lgkmcnt(0)
	v_mfma_f32_16x16x32_bf16 v[124:127], v[128:131], v[176:179], v[124:127]
	v_mfma_f32_16x16x32_bf16 v[120:123], v[136:139], v[176:179], v[120:123]
	v_mfma_f32_16x16x32_bf16 v[112:115], v[128:131], v[184:187], v[112:115]
	v_mfma_f32_16x16x32_bf16 v[104:107], v[136:139], v[184:187], v[104:107]
	v_mfma_f32_16x16x32_bf16 v[100:103], v[128:131], v[192:195], v[100:103]
	v_mfma_f32_16x16x32_bf16 v[92:95], v[136:139], v[192:195], v[92:95]
	v_mfma_f32_16x16x32_bf16 v[84:87], v[128:131], v[200:203], v[84:87]
	v_mfma_f32_16x16x32_bf16 v[76:79], v[136:139], v[200:203], v[76:79]
	v_mfma_f32_16x16x32_bf16 v[124:127], v[132:135], v[180:183], v[124:127]
	v_mfma_f32_16x16x32_bf16 v[120:123], v[140:143], v[180:183], v[120:123]
	v_mfma_f32_16x16x32_bf16 v[112:115], v[132:135], v[188:191], v[112:115]
	v_mfma_f32_16x16x32_bf16 v[104:107], v[140:143], v[188:191], v[104:107]
	v_mfma_f32_16x16x32_bf16 v[100:103], v[132:135], v[196:199], v[100:103]
	v_mfma_f32_16x16x32_bf16 v[92:95], v[140:143], v[196:199], v[92:95]
	v_mfma_f32_16x16x32_bf16 v[84:87], v[132:135], v[204:207], v[84:87]
	v_mfma_f32_16x16x32_bf16 v[76:79], v[140:143], v[204:207], v[76:79]
	v_mfma_f32_16x16x32_bf16 v[116:119], v[150:153], v[176:179], v[116:119]
	v_mfma_f32_16x16x32_bf16 v[108:111], v[168:171], v[176:179], v[108:111]
	v_mfma_f32_16x16x32_bf16 v[96:99], v[150:153], v[184:187], v[96:99]
	v_mfma_f32_16x16x32_bf16 v[88:91], v[168:171], v[184:187], v[88:91]
	v_mfma_f32_16x16x32_bf16 v[80:83], v[150:153], v[192:195], v[80:83]
	v_mfma_f32_16x16x32_bf16 v[72:75], v[168:171], v[192:195], v[72:75]
	v_mfma_f32_16x16x32_bf16 v[68:71], v[150:153], v[200:203], v[68:71]
	v_mfma_f32_16x16x32_bf16 v[64:67], v[168:171], v[200:203], v[64:67]
	v_mfma_f32_16x16x32_bf16 v[116:119], v[164:167], v[180:183], v[116:119]
	v_mfma_f32_16x16x32_bf16 v[108:111], v[172:175], v[180:183], v[108:111]
	v_mfma_f32_16x16x32_bf16 v[96:99], v[164:167], v[188:191], v[96:99]
	v_mfma_f32_16x16x32_bf16 v[88:91], v[172:175], v[188:191], v[88:91]
	v_mfma_f32_16x16x32_bf16 v[80:83], v[164:167], v[196:199], v[80:83]
	v_mfma_f32_16x16x32_bf16 v[72:75], v[172:175], v[196:199], v[72:75]
	v_mfma_f32_16x16x32_bf16 v[68:71], v[164:167], v[204:207], v[68:71]
	v_mfma_f32_16x16x32_bf16 v[64:67], v[172:175], v[204:207], v[64:67]
	s_barrier
	v_mov_b32_e32 v144, v157
	s_add_i32 s79, s55, s73
	ds_read_b128 v[176:179], v163 offset:16384
	ds_read_b128 v[180:183], v163 offset:17408
	ds_read_b128 v[184:187], v163 offset:18432
	ds_read_b128 v[188:191], v163 offset:19456
	ds_read_b128 v[192:195], v163 offset:20480
	ds_read_b128 v[196:199], v163 offset:21504
	ds_read_b128 v[200:203], v163 offset:22528
	ds_read_b128 v[204:207], v163 offset:23552
	s_mov_b32 m0, s79
	s_nop 0
	global_load_lds_dwordx4 v144, s[42:43]
	v_mov_b32_e32 v144, v159
	s_add_i32 m0, s79, 0x2000
	s_add_u32 s80, s42, 0x80000
	global_load_lds_dwordx4 v144, s[42:43]
	s_addc_u32 s81, s43, 0
	v_mov_b32_e32 v144, v157
	s_add_i32 s79, s61, s73
	s_mov_b32 m0, s79
	s_nop 0
	global_load_lds_dwordx4 v144, s[80:81]
	v_mov_b32_e32 v144, v159
	s_add_i32 m0, s79, 0x2000
	s_nop 0
	global_load_lds_dwordx4 v144, s[80:81]
	v_mov_b32_e32 v144, v156
	s_mov_b32 m0, s31
	s_nop 0
	global_load_lds_dwordx4 v144, s[40:41]
	v_mov_b32_e32 v144, v158
	s_mov_b32 m0, s44
	s_nop 0
	global_load_lds_dwordx4 v144, s[40:41]
	s_waitcnt vmcnt(8)
	s_waitcnt lgkmcnt(0)
	s_barrier
	s_waitcnt lgkmcnt(0)
	v_mfma_f32_16x16x32_bf16 v[60:63], v[128:131], v[176:179], v[60:63]
	v_mfma_f32_16x16x32_bf16 v[56:59], v[136:139], v[176:179], v[56:59]
	v_mfma_f32_16x16x32_bf16 v[52:55], v[128:131], v[184:187], v[52:55]
	v_mfma_f32_16x16x32_bf16 v[44:47], v[136:139], v[184:187], v[44:47]
	v_mfma_f32_16x16x32_bf16 v[36:39], v[128:131], v[192:195], v[36:39]
	v_mfma_f32_16x16x32_bf16 v[28:31], v[136:139], v[192:195], v[28:31]
	v_mfma_f32_16x16x32_bf16 v[20:23], v[128:131], v[200:203], v[20:23]
	v_mfma_f32_16x16x32_bf16 v[12:15], v[136:139], v[200:203], v[12:15]
	v_mfma_f32_16x16x32_bf16 v[60:63], v[132:135], v[180:183], v[60:63]
	v_mfma_f32_16x16x32_bf16 v[56:59], v[140:143], v[180:183], v[56:59]
	v_mfma_f32_16x16x32_bf16 v[52:55], v[132:135], v[188:191], v[52:55]
	v_mfma_f32_16x16x32_bf16 v[44:47], v[140:143], v[188:191], v[44:47]
	v_mfma_f32_16x16x32_bf16 v[36:39], v[132:135], v[196:199], v[36:39]
	v_mfma_f32_16x16x32_bf16 v[28:31], v[140:143], v[196:199], v[28:31]
	v_mfma_f32_16x16x32_bf16 v[20:23], v[132:135], v[204:207], v[20:23]
	v_mfma_f32_16x16x32_bf16 v[12:15], v[140:143], v[204:207], v[12:15]
	v_mfma_f32_16x16x32_bf16 v[48:51], v[150:153], v[176:179], v[48:51]
	v_mfma_f32_16x16x32_bf16 v[40:43], v[168:171], v[176:179], v[40:43]
	v_mfma_f32_16x16x32_bf16 v[32:35], v[150:153], v[184:187], v[32:35]
	v_mfma_f32_16x16x32_bf16 v[24:27], v[168:171], v[184:187], v[24:27]
	v_mfma_f32_16x16x32_bf16 v[16:19], v[150:153], v[192:195], v[16:19]
	v_mfma_f32_16x16x32_bf16 v[8:11], v[168:171], v[192:195], v[8:11]
	v_mfma_f32_16x16x32_bf16 v[4:7], v[150:153], v[200:203], v[4:7]
	v_mfma_f32_16x16x32_bf16 v[0:3], v[168:171], v[200:203], v[0:3]
	v_mfma_f32_16x16x32_bf16 v[48:51], v[164:167], v[180:183], v[48:51]
	v_mfma_f32_16x16x32_bf16 v[40:43], v[172:175], v[180:183], v[40:43]
	v_mfma_f32_16x16x32_bf16 v[32:35], v[164:167], v[188:191], v[32:35]
	v_mfma_f32_16x16x32_bf16 v[24:27], v[172:175], v[188:191], v[24:27]
	v_mfma_f32_16x16x32_bf16 v[16:19], v[164:167], v[196:199], v[16:19]
	v_mfma_f32_16x16x32_bf16 v[8:11], v[172:175], v[196:199], v[8:11]
	v_mfma_f32_16x16x32_bf16 v[4:7], v[164:167], v[204:207], v[4:7]
	v_mfma_f32_16x16x32_bf16 v[0:3], v[172:175], v[204:207], v[0:3]
	s_barrier
; #define PG8_STAGE(bufoff, gbase, voff) do { _Pragma("unroll") for (int _i = 0; _i < 2; ++_i) { unsigned _vo = (voff)[_i]; asm volatile("" : "+v"(_vo));   \
;         __builtin_amdgcn_global_load_lds((const unsigned*)((const char*)(gbase) + _vo), (LAS unsigned*)(lds + (bufoff) + ldsw + _i * 8192), 16, 0, 0); } } while (0)
; #define PG8_LDA(dst, b, h) do { _Pragma("unroll") for (int m = 0; m < 4; ++m) _Pragma("unroll") for (int k = 0; k < 2; ++k) dst[m][k] = *(const LAS bf16x8*)(lds + PG8_SA(b, h) + aoff + m * 2048 + k * 1024); } while (0)
; #define PG8_LDB(dst, b, h) do { _Pragma("unroll") for (int n = 0; n < 2; ++n) _Pragma("unroll") for (int k = 0; k < 2; ++k) dst[n][k] = *(const LAS bf16x8*)(lds + PG8_SB(b, h) + boff + n * 2048 + k * 1024); } while (0)
; #define PG8_WAIT_V(n) asm volatile("s_waitcnt vmcnt(" #n ")" ::: "memory")
; #define PG8_WAIT_L(n) asm volatile("s_waitcnt lgkmcnt(" #n ")" ::: "memory")
; #define PG8_BAR __builtin_amdgcn_s_barrier()
; #define PG8_SCHED __builtin_amdgcn_sched_barrier(0)
; template <bool F8 = false>
; __device__ __forceinline__ void gemm_phase(LAS unsigned char* lds, const int K, const Sched& S, const Epi& E, const int wave_s) {
;     ...
;             PG8_LDB(B0, 1, 0); PG8_LDB(B1, 1, 1); PG8_SCHED; PG8_LDA(At, 1, 0); PG8_STAGE(PG8_SA(0, 1), a2 + hstepA, voffA);
;             PG8_WAIT_V(8); PG8_WAIT_L(0); PG8_BAR; PG8_MMA(0, 0, At, B0); PG8_MMA(0, 1, At, B1); PG8_BAR; PG8_SCHED;
	s_add_i32 s79, 0, 0x18000
	s_add_i32 s82, 0, 0x1c000
	v_add_u32_e32 v140, s79, v160
	v_add_u32_e32 v144, s82, v160
	ds_read_b128 v[128:131], v140
	ds_read_b128 v[132:135], v140 offset:1024
	ds_read_b128 v[136:139], v140 offset:2048
	ds_read_b128 v[140:143], v140 offset:3072
	ds_read_b128 v[150:153], v144
	ds_read_b128 v[164:167], v144 offset:1024
	ds_read_b128 v[168:171], v144 offset:2048
	ds_read_b128 v[172:175], v144 offset:3072
	s_add_u32 s80, s40, 0x80000
	v_mov_b32_e32 v144, v156
	s_mov_b32 m0, s45
	ds_read_b128 v[176:179], v163 offset:32768
	ds_read_b128 v[180:183], v163 offset:33792
	ds_read_b128 v[184:187], v163 offset:34816
	ds_read_b128 v[188:191], v163 offset:35840
	ds_read_b128 v[192:195], v163 offset:36864
	ds_read_b128 v[196:199], v163 offset:37888
	ds_read_b128 v[200:203], v163 offset:38912
	ds_read_b128 v[204:207], v163 offset:39936
	s_addc_u32 s81, s41, 0
	s_nop 0
	global_load_lds_dwordx4 v144, s[80:81]
	v_mov_b32_e32 v144, v158
	s_mov_b32 m0, s46
	s_nop 0
	global_load_lds_dwordx4 v144, s[80:81]
	s_waitcnt vmcnt(8)
	s_waitcnt lgkmcnt(0)
	s_barrier
	s_waitcnt lgkmcnt(0)
	v_mfma_f32_16x16x32_bf16 v[124:127], v[128:131], v[176:179], v[124:127]
	v_mfma_f32_16x16x32_bf16 v[120:123], v[136:139], v[176:179], v[120:123]
	v_mfma_f32_16x16x32_bf16 v[112:115], v[128:131], v[184:187], v[112:115]
	v_mfma_f32_16x16x32_bf16 v[104:107], v[136:139], v[184:187], v[104:107]
	v_mfma_f32_16x16x32_bf16 v[100:103], v[128:131], v[192:195], v[100:103]
	v_mfma_f32_16x16x32_bf16 v[92:95], v[136:139], v[192:195], v[92:95]
	v_mfma_f32_16x16x32_bf16 v[84:87], v[128:131], v[200:203], v[84:87]
	v_mfma_f32_16x16x32_bf16 v[76:79], v[136:139], v[200:203], v[76:79]
	v_mfma_f32_16x16x32_bf16 v[124:127], v[132:135], v[180:183], v[124:127]
	v_mfma_f32_16x16x32_bf16 v[120:123], v[140:143], v[180:183], v[120:123]
	v_mfma_f32_16x16x32_bf16 v[112:115], v[132:135], v[188:191], v[112:115]
	v_mfma_f32_16x16x32_bf16 v[104:107], v[140:143], v[188:191], v[104:107]
	v_mfma_f32_16x16x32_bf16 v[100:103], v[132:135], v[196:199], v[100:103]
	v_mfma_f32_16x16x32_bf16 v[92:95], v[140:143], v[196:199], v[92:95]
	v_mfma_f32_16x16x32_bf16 v[84:87], v[132:135], v[204:207], v[84:87]
	v_mfma_f32_16x16x32_bf16 v[76:79], v[140:143], v[204:207], v[76:79]
	v_mfma_f32_16x16x32_bf16 v[116:119], v[150:153], v[176:179], v[116:119]
	v_mfma_f32_16x16x32_bf16 v[108:111], v[168:171], v[176:179], v[108:111]
	v_mfma_f32_16x16x32_bf16 v[96:99], v[150:153], v[184:187], v[96:99]
	v_mfma_f32_16x16x32_bf16 v[88:91], v[168:171], v[184:187], v[88:91]
	v_mfma_f32_16x16x32_bf16 v[80:83], v[150:153], v[192:195], v[80:83]
	v_mfma_f32_16x16x32_bf16 v[72:75], v[168:171], v[192:195], v[72:75]
	v_mfma_f32_16x16x32_bf16 v[68:71], v[150:153], v[200:203], v[68:71]
	v_mfma_f32_16x16x32_bf16 v[64:67], v[168:171], v[200:203], v[64:67]
	v_mfma_f32_16x16x32_bf16 v[116:119], v[164:167], v[180:183], v[116:119]
	v_mfma_f32_16x16x32_bf16 v[108:111], v[172:175], v[180:183], v[108:111]
	v_mfma_f32_16x16x32_bf16 v[96:99], v[164:167], v[188:191], v[96:99]
	v_mfma_f32_16x16x32_bf16 v[88:91], v[172:175], v[188:191], v[88:91]
	v_mfma_f32_16x16x32_bf16 v[80:83], v[164:167], v[196:199], v[80:83]
	v_mfma_f32_16x16x32_bf16 v[72:75], v[172:175], v[196:199], v[72:75]
	v_mfma_f32_16x16x32_bf16 v[68:71], v[164:167], v[204:207], v[68:71]
	v_mfma_f32_16x16x32_bf16 v[64:67], v[172:175], v[204:207], v[64:67]
	s_barrier
; #define PG8_STAGE(bufoff, gbase, voff) do { _Pragma("unroll") for (int _i = 0; _i < 2; ++_i) { unsigned _vo = (voff)[_i]; asm volatile("" : "+v"(_vo));   \
;         __builtin_amdgcn_global_load_lds((const unsigned*)((const char*)(gbase) + _vo), (LAS unsigned*)(lds + (bufoff) + ldsw + _i * 8192), 16, 0, 0); } } while (0)
; #define PG8_LDA(dst, b, h) do { _Pragma("unroll") for (int m = 0; m < 4; ++m) _Pragma("unroll") for (int k = 0; k < 2; ++k) dst[m][k] = *(const LAS bf16x8*)(lds + PG8_SA(b, h) + aoff + m * 2048 + k * 1024); } while (0)
; #define PG8_WAIT_V(n) asm volatile("s_waitcnt vmcnt(" #n ")" ::: "memory")
; #define PG8_WAIT_L(n) asm volatile("s_waitcnt lgkmcnt(" #n ")" ::: "memory")
; #define PG8_BAR __builtin_amdgcn_s_barrier()
; #define PG8_SCHED __builtin_amdgcn_sched_barrier(0)
; template <bool F8 = false>
; __device__ __forceinline__ void gemm_phase(LAS unsigned char* lds, const int K, const Sched& S, const Epi& E, const int wave_s) {
;     ...
;             PG8_LDA(At, 1, 1); PG8_STAGE(PG8_SB(1, 0), b3, voffB); PG8_STAGE(PG8_SB(1, 1), b3 + hstepB, voffB); PG8_STAGE(PG8_SA(1, 0), a3, voffA);
;             PG8_WAIT_V(8); PG8_WAIT_L(0); PG8_BAR; PG8_MMA(1, 0, At, B0); PG8_MMA(1, 1, At, B1); PG8_BAR; PG8_SCHED;
;         }
;         if (align) { if (wr == 0) PG8_BAR; }
	v_mov_b32_e32 v144, v157
	ds_read_b128 v[176:179], v163 offset:49152
	ds_read_b128 v[180:183], v163 offset:50176
	ds_read_b128 v[184:187], v163 offset:51200
	ds_read_b128 v[188:191], v163 offset:52224
	ds_read_b128 v[192:195], v163 offset:53248
	ds_read_b128 v[196:199], v163 offset:54272
	ds_read_b128 v[200:203], v163 offset:55296
	ds_read_b128 v[204:207], v163 offset:56320
	s_add_i32 s79, s79, s73
	v_lshl_add_u64 v[154:155], s[42:43], 0, v[144:145]
	v_lshl_add_u64 v[154:155], v[154:155], 0, s[12:13]
	s_mov_b32 m0, s79
	v_mov_b32_e32 v144, v159
	global_load_lds_dwordx4 v[154:155], off
	s_add_i32 m0, s79, 0x2000
	s_nop 0
	v_lshl_add_u64 v[154:155], s[42:43], 0, v[144:145]
	s_add_u32 s42, s42, 0x80080
	v_lshl_add_u64 v[154:155], v[154:155], 0, s[12:13]
	s_addc_u32 s43, s43, 0
	v_mov_b32_e32 v144, v157
	s_add_i32 s79, s82, s73
	global_load_lds_dwordx4 v[154:155], off
	s_mov_b32 m0, s79
	s_nop 0
	global_load_lds_dwordx4 v144, s[42:43]
	v_mov_b32_e32 v144, v159
	s_add_i32 m0, s79, 0x2000
	s_nop 0
	global_load_lds_dwordx4 v144, s[42:43]
	v_mov_b32_e32 v144, v156
	s_mov_b32 m0, s48
	v_lshl_add_u64 v[154:155], s[40:41], 0, v[144:145]
	v_lshl_add_u64 v[154:155], v[154:155], 0, s[12:13]
	v_mov_b32_e32 v144, v158
	global_load_lds_dwordx4 v[154:155], off
	s_mov_b32 m0, s49
	v_lshl_add_u64 v[154:155], s[40:41], 0, v[144:145]
	v_lshl_add_u64 v[154:155], v[154:155], 0, s[12:13]
	global_load_lds_dwordx4 v[154:155], off
	s_waitcnt vmcnt(8)
	s_waitcnt lgkmcnt(0)
	s_barrier
	s_waitcnt lgkmcnt(0)
	v_mfma_f32_16x16x32_bf16 v[60:63], v[128:131], v[176:179], v[60:63]
	v_mfma_f32_16x16x32_bf16 v[56:59], v[136:139], v[176:179], v[56:59]
	v_mfma_f32_16x16x32_bf16 v[52:55], v[128:131], v[184:187], v[52:55]
	v_mfma_f32_16x16x32_bf16 v[44:47], v[136:139], v[184:187], v[44:47]
	v_mfma_f32_16x16x32_bf16 v[36:39], v[128:131], v[192:195], v[36:39]
	v_mfma_f32_16x16x32_bf16 v[28:31], v[136:139], v[192:195], v[28:31]
	v_mfma_f32_16x16x32_bf16 v[20:23], v[128:131], v[200:203], v[20:23]
	v_mfma_f32_16x16x32_bf16 v[12:15], v[136:139], v[200:203], v[12:15]
	v_mfma_f32_16x16x32_bf16 v[60:63], v[132:135], v[180:183], v[60:63]
	v_mfma_f32_16x16x32_bf16 v[56:59], v[140:143], v[180:183], v[56:59]
	v_mfma_f32_16x16x32_bf16 v[52:55], v[132:135], v[188:191], v[52:55]
	v_mfma_f32_16x16x32_bf16 v[44:47], v[140:143], v[188:191], v[44:47]
	v_mfma_f32_16x16x32_bf16 v[36:39], v[132:135], v[196:199], v[36:39]
	v_mfma_f32_16x16x32_bf16 v[28:31], v[140:143], v[196:199], v[28:31]
	v_mfma_f32_16x16x32_bf16 v[20:23], v[132:135], v[204:207], v[20:23]
	v_mfma_f32_16x16x32_bf16 v[12:15], v[140:143], v[204:207], v[12:15]
	v_mfma_f32_16x16x32_bf16 v[48:51], v[150:153], v[176:179], v[48:51]
	v_mfma_f32_16x16x32_bf16 v[40:43], v[168:171], v[176:179], v[40:43]
	v_mfma_f32_16x16x32_bf16 v[32:35], v[150:153], v[184:187], v[32:35]
	v_mfma_f32_16x16x32_bf16 v[24:27], v[168:171], v[184:187], v[24:27]
	v_mfma_f32_16x16x32_bf16 v[16:19], v[150:153], v[192:195], v[16:19]
	v_mfma_f32_16x16x32_bf16 v[8:11], v[168:171], v[192:195], v[8:11]
	v_mfma_f32_16x16x32_bf16 v[4:7], v[150:153], v[200:203], v[4:7]
	v_mfma_f32_16x16x32_bf16 v[0:3], v[168:171], v[200:203], v[0:3]
	v_mfma_f32_16x16x32_bf16 v[48:51], v[164:167], v[180:183], v[48:51]
	v_mfma_f32_16x16x32_bf16 v[40:43], v[172:175], v[180:183], v[40:43]
	v_mfma_f32_16x16x32_bf16 v[32:35], v[164:167], v[188:191], v[32:35]
	v_mfma_f32_16x16x32_bf16 v[24:27], v[172:175], v[188:191], v[24:27]
	v_mfma_f32_16x16x32_bf16 v[16:19], v[164:167], v[196:199], v[16:19]
	v_mfma_f32_16x16x32_bf16 v[8:11], v[172:175], v[196:199], v[8:11]
	v_mfma_f32_16x16x32_bf16 v[4:7], v[164:167], v[204:207], v[4:7]
	v_mfma_f32_16x16x32_bf16 v[0:3], v[172:175], v[204:207], v[0:3]
	s_barrier
	s_add_i32 s69, s69, 2
	s_add_u32 s38, s38, 0x100
	s_addc_u32 s39, s39, 0
	s_add_u32 s23, s23, 0x100
	s_addc_u32 s63, s63, 0
	s_cmp_gt_u32 s69, 29
	s_cbranch_scc0 .LBB0_1709
	s_setprio 0
	s_and_b64 vcc, exec, s[18:19]
	s_cbranch_vccz .LBB0_1712
	s_barrier

; #define PG8_STAGE(bufoff, gbase, voff) do { _Pragma("unroll") for (int _i = 0; _i < 2; ++_i) { unsigned _vo = (voff)[_i]; asm volatile("" : "+v"(_vo));   \
;         __builtin_amdgcn_global_load_lds((const unsigned*)((const char*)(gbase) + _vo), (LAS unsigned*)(lds + (bufoff) + ldsw + _i * 8192), 16, 0, 0); } } while (0)
; #define PG8_LDA(dst, b, h) do { _Pragma("unroll") for (int m = 0; m < 4; ++m) _Pragma("unroll") for (int k = 0; k < 2; ++k) dst[m][k] = *(const LAS bf16x8*)(lds + PG8_SA(b, h) + aoff + m * 2048 + k * 1024); } while (0)
; #define PG8_LDB(dst, b, h) do { _Pragma("unroll") for (int n = 0; n < 2; ++n) _Pragma("unroll") for (int k = 0; k < 2; ++k) dst[n][k] = *(const LAS bf16x8*)(lds + PG8_SB(b, h) + boff + n * 2048 + k * 1024); } while (0)
; #define PG8_WAIT_V(n) asm volatile("s_waitcnt vmcnt(" #n ")" ::: "memory")
; #define PG8_WAIT_L(n) asm volatile("s_waitcnt lgkmcnt(" #n ")" ::: "memory")
; #define PG8_BAR __builtin_amdgcn_s_barrier()
; #define PG8_SCHED __builtin_amdgcn_sched_barrier(0)
; template <bool F8 = false>
; __device__ __forceinline__ void gemm_phase(LAS unsigned char* lds, const int K, const Sched& S, const Epi& E, const int wave_s) {
;     ...
;             PG8_LDB(B0, 0, 0); PG8_LDB(B1, 0, 1); PG8_SCHED; PG8_LDA(At, 0, 0); PG8_STAGE(PG8_SA(1, 1), a1 + hstepA, voffA);
;             PG8_WAIT_V(8); PG8_WAIT_L(0); PG8_BAR; PG8_MMA(0, 0, At, B0); PG8_MMA(0, 1, At, B1); PG8_BAR; PG8_SCHED;
;             PG8_LDA(At, 0, 1); PG8_STAGE(PG8_SB(0, 0), b2, voffB); PG8_STAGE(PG8_SB(0, 1), b2 + hstepB, voffB); PG8_STAGE(PG8_SA(0, 0), a2, voffA);
;             PG8_WAIT_V(8); PG8_WAIT_L(0); PG8_BAR; PG8_MMA(1, 0, At, B0); PG8_MMA(1, 1, At, B1); PG8_BAR; PG8_SCHED;
.Lmy_prio6:
	ds_read_b128 v[144:147], v141
	ds_read_b128 v[148:151], v141 offset:1024
	ds_read_b128 v[152:155], v141 offset:2048
	ds_read_b128 v[156:159], v141 offset:3072
	ds_read_b128 v[160:163], v142
	ds_read_b128 v[164:167], v142 offset:1024
	ds_read_b128 v[168:171], v142 offset:2048
	ds_read_b128 v[172:175], v142 offset:3072
	s_add_u32 s40, s38, 0xfffc0080
	s_addc_u32 s41, s39, -1
	s_cmp_eq_u32 s63, 12
	s_cselect_b32 s41, s35, s41
	s_cselect_b32 s40, s34, s40
	s_cselect_b32 s43, s37, s62
	s_cselect_b32 s42, s36, s25
	v_mov_b32_e32 v128, v136
	ds_read_b128 v[176:179], v143
	ds_read_b128 v[180:183], v143 offset:1024
	ds_read_b128 v[184:187], v143 offset:2048
	ds_read_b128 v[188:191], v143 offset:3072
	ds_read_b128 v[192:195], v143 offset:4096
	ds_read_b128 v[196:199], v143 offset:5120
	ds_read_b128 v[200:203], v143 offset:6144
	ds_read_b128 v[204:207], v143 offset:7168
	s_add_i32 m0, s46, 0xc000
	s_nop 0
	global_load_lds_dwordx4 v128, s[38:39]
	v_mov_b32_e32 v128, v138
	s_add_i32 m0, s46, 0xe000
	s_nop 0
	global_load_lds_dwordx4 v128, s[38:39]
	s_waitcnt vmcnt(8)
	s_waitcnt lgkmcnt(0)
	s_barrier
	s_waitcnt lgkmcnt(0)
	v_mfma_i32_16x16x64_i8 v[124:127], v[144:147], v[176:179], v[124:127]
	v_mfma_i32_16x16x64_i8 v[120:123], v[152:155], v[176:179], v[120:123]
	v_mfma_i32_16x16x64_i8 v[108:111], v[144:147], v[184:187], v[108:111]
	v_mfma_i32_16x16x64_i8 v[104:107], v[152:155], v[184:187], v[104:107]
	v_mfma_i32_16x16x64_i8 v[92:95], v[144:147], v[192:195], v[92:95]
	v_mfma_i32_16x16x64_i8 v[88:91], v[152:155], v[192:195], v[88:91]
	v_mfma_i32_16x16x64_i8 v[76:79], v[144:147], v[200:203], v[76:79]
	v_mfma_i32_16x16x64_i8 v[72:75], v[152:155], v[200:203], v[72:75]
	v_mfma_i32_16x16x64_i8 v[124:127], v[148:151], v[180:183], v[124:127]
	v_mfma_i32_16x16x64_i8 v[120:123], v[156:159], v[180:183], v[120:123]
	v_mfma_i32_16x16x64_i8 v[108:111], v[148:151], v[188:191], v[108:111]
	v_mfma_i32_16x16x64_i8 v[104:107], v[156:159], v[188:191], v[104:107]
	v_mfma_i32_16x16x64_i8 v[92:95], v[148:151], v[196:199], v[92:95]
	v_mfma_i32_16x16x64_i8 v[88:91], v[156:159], v[196:199], v[88:91]
	v_mfma_i32_16x16x64_i8 v[76:79], v[148:151], v[204:207], v[76:79]
	v_mfma_i32_16x16x64_i8 v[72:75], v[156:159], v[204:207], v[72:75]
	v_mfma_i32_16x16x64_i8 v[116:119], v[160:163], v[176:179], v[116:119]
	v_mfma_i32_16x16x64_i8 v[112:115], v[168:171], v[176:179], v[112:115]
	v_mfma_i32_16x16x64_i8 v[100:103], v[160:163], v[184:187], v[100:103]
	v_mfma_i32_16x16x64_i8 v[96:99], v[168:171], v[184:187], v[96:99]
	v_mfma_i32_16x16x64_i8 v[84:87], v[160:163], v[192:195], v[84:87]
	v_mfma_i32_16x16x64_i8 v[80:83], v[168:171], v[192:195], v[80:83]
	v_mfma_i32_16x16x64_i8 v[68:71], v[160:163], v[200:203], v[68:71]
	v_mfma_i32_16x16x64_i8 v[64:67], v[168:171], v[200:203], v[64:67]
	v_mfma_i32_16x16x64_i8 v[116:119], v[164:167], v[180:183], v[116:119]
	v_mfma_i32_16x16x64_i8 v[112:115], v[172:175], v[180:183], v[112:115]
	v_mfma_i32_16x16x64_i8 v[100:103], v[164:167], v[188:191], v[100:103]
	v_mfma_i32_16x16x64_i8 v[96:99], v[172:175], v[188:191], v[96:99]
	v_mfma_i32_16x16x64_i8 v[84:87], v[164:167], v[196:199], v[84:87]
	v_mfma_i32_16x16x64_i8 v[80:83], v[172:175], v[196:199], v[80:83]
	v_mfma_i32_16x16x64_i8 v[68:71], v[164:167], v[204:207], v[68:71]
	v_mfma_i32_16x16x64_i8 v[64:67], v[172:175], v[204:207], v[64:67]
	s_barrier
	v_mov_b32_e32 v128, v137
	s_add_i32 s80, s70, s73
	ds_read_b128 v[176:179], v143 offset:16384
	ds_read_b128 v[180:183], v143 offset:17408
	ds_read_b128 v[184:187], v143 offset:18432
	ds_read_b128 v[188:191], v143 offset:19456
	ds_read_b128 v[192:195], v143 offset:20480
	ds_read_b128 v[196:199], v143 offset:21504
	ds_read_b128 v[200:203], v143 offset:22528
	ds_read_b128 v[204:207], v143 offset:23552
	s_mov_b32 m0, s80
	s_nop 0
	global_load_lds_dwordx4 v128, s[42:43]
	v_mov_b32_e32 v128, v139
	s_add_i32 m0, s80, 0x2000
	s_add_u32 s80, s42, 0x40000
	global_load_lds_dwordx4 v128, s[42:43]
	s_addc_u32 s81, s43, 0
	v_mov_b32_e32 v128, v137
	s_add_i32 s82, s76, s73
	s_mov_b32 m0, s82
	s_nop 0
	global_load_lds_dwordx4 v128, s[80:81]
	v_mov_b32_e32 v128, v139
	s_add_i32 m0, s82, 0x2000
	s_nop 0
	global_load_lds_dwordx4 v128, s[80:81]
	v_mov_b32_e32 v128, v136
	s_mov_b32 m0, s46
	s_nop 0
	global_load_lds_dwordx4 v128, s[40:41]
	v_mov_b32_e32 v128, v138
	s_mov_b32 m0, s47
	s_nop 0
	global_load_lds_dwordx4 v128, s[40:41]
	s_waitcnt vmcnt(8)
	s_waitcnt lgkmcnt(0)
	s_barrier
	s_waitcnt lgkmcnt(0)
	v_mfma_i32_16x16x64_i8 v[60:63], v[144:147], v[176:179], v[60:63]
	v_mfma_i32_16x16x64_i8 v[56:59], v[152:155], v[176:179], v[56:59]
	v_mfma_i32_16x16x64_i8 v[44:47], v[144:147], v[184:187], v[44:47]
	v_mfma_i32_16x16x64_i8 v[40:43], v[152:155], v[184:187], v[40:43]
	v_mfma_i32_16x16x64_i8 v[28:31], v[144:147], v[192:195], v[28:31]
	v_mfma_i32_16x16x64_i8 v[24:27], v[152:155], v[192:195], v[24:27]
	v_mfma_i32_16x16x64_i8 v[12:15], v[144:147], v[200:203], v[12:15]
	v_mfma_i32_16x16x64_i8 v[8:11], v[152:155], v[200:203], v[8:11]
	v_mfma_i32_16x16x64_i8 v[60:63], v[148:151], v[180:183], v[60:63]
	v_mfma_i32_16x16x64_i8 v[56:59], v[156:159], v[180:183], v[56:59]
	v_mfma_i32_16x16x64_i8 v[44:47], v[148:151], v[188:191], v[44:47]
	v_mfma_i32_16x16x64_i8 v[40:43], v[156:159], v[188:191], v[40:43]
	v_mfma_i32_16x16x64_i8 v[28:31], v[148:151], v[196:199], v[28:31]
	v_mfma_i32_16x16x64_i8 v[24:27], v[156:159], v[196:199], v[24:27]
	v_mfma_i32_16x16x64_i8 v[12:15], v[148:151], v[204:207], v[12:15]
	v_mfma_i32_16x16x64_i8 v[8:11], v[156:159], v[204:207], v[8:11]
	v_mfma_i32_16x16x64_i8 v[52:55], v[160:163], v[176:179], v[52:55]
	v_mfma_i32_16x16x64_i8 v[48:51], v[168:171], v[176:179], v[48:51]
	v_mfma_i32_16x16x64_i8 v[36:39], v[160:163], v[184:187], v[36:39]
	v_mfma_i32_16x16x64_i8 v[32:35], v[168:171], v[184:187], v[32:35]
	v_mfma_i32_16x16x64_i8 v[20:23], v[160:163], v[192:195], v[20:23]
	v_mfma_i32_16x16x64_i8 v[16:19], v[168:171], v[192:195], v[16:19]
	v_mfma_i32_16x16x64_i8 v[4:7], v[160:163], v[200:203], v[4:7]
	v_mfma_i32_16x16x64_i8 v[0:3], v[168:171], v[200:203], v[0:3]
	v_mfma_i32_16x16x64_i8 v[52:55], v[164:167], v[180:183], v[52:55]
	v_mfma_i32_16x16x64_i8 v[48:51], v[172:175], v[180:183], v[48:51]
	v_mfma_i32_16x16x64_i8 v[36:39], v[164:167], v[188:191], v[36:39]
	v_mfma_i32_16x16x64_i8 v[32:35], v[172:175], v[188:191], v[32:35]
	v_mfma_i32_16x16x64_i8 v[20:23], v[164:167], v[196:199], v[20:23]
	v_mfma_i32_16x16x64_i8 v[16:19], v[172:175], v[196:199], v[16:19]
	v_mfma_i32_16x16x64_i8 v[4:7], v[164:167], v[204:207], v[4:7]
	v_mfma_i32_16x16x64_i8 v[0:3], v[172:175], v[204:207], v[0:3]
	s_barrier
; #define PG8_STAGE(bufoff, gbase, voff) do { _Pragma("unroll") for (int _i = 0; _i < 2; ++_i) { unsigned _vo = (voff)[_i]; asm volatile("" : "+v"(_vo));   \
;         __builtin_amdgcn_global_load_lds((const unsigned*)((const char*)(gbase) + _vo), (LAS unsigned*)(lds + (bufoff) + ldsw + _i * 8192), 16, 0, 0); } } while (0)
; #define PG8_LDA(dst, b, h) do { _Pragma("unroll") for (int m = 0; m < 4; ++m) _Pragma("unroll") for (int k = 0; k < 2; ++k) dst[m][k] = *(const LAS bf16x8*)(lds + PG8_SA(b, h) + aoff + m * 2048 + k * 1024); } while (0)
; #define PG8_LDB(dst, b, h) do { _Pragma("unroll") for (int n = 0; n < 2; ++n) _Pragma("unroll") for (int k = 0; k < 2; ++k) dst[n][k] = *(const LAS bf16x8*)(lds + PG8_SB(b, h) + boff + n * 2048 + k * 1024); } while (0)
; #define PG8_WAIT_V(n) asm volatile("s_waitcnt vmcnt(" #n ")" ::: "memory")
; #define PG8_WAIT_L(n) asm volatile("s_waitcnt lgkmcnt(" #n ")" ::: "memory")
; #define PG8_BAR __builtin_amdgcn_s_barrier()
; #define PG8_SCHED __builtin_amdgcn_sched_barrier(0)
; template <bool F8 = false>
; __device__ __forceinline__ void gemm_phase(LAS unsigned char* lds, const int K, const Sched& S, const Epi& E, const int wave_s) {
;     ...
;             PG8_LDB(B0, 1, 0); PG8_LDB(B1, 1, 1); PG8_SCHED; PG8_LDA(At, 1, 0); PG8_STAGE(PG8_SA(0, 1), a2 + hstepA, voffA);
;             PG8_WAIT_V(8); PG8_WAIT_L(0); PG8_BAR; PG8_MMA(0, 0, At, B0); PG8_MMA(0, 1, At, B1); PG8_BAR; PG8_SCHED;
	s_add_i32 s82, 0, 0x18000
	v_add_u32_e32 v128, s82, v140
	s_add_i32 s83, 0, 0x1c000
	ds_read_b128 v[144:147], v128
	ds_read_b128 v[148:151], v128 offset:1024
	ds_read_b128 v[152:155], v128 offset:2048
	ds_read_b128 v[156:159], v128 offset:3072
	v_add_u32_e32 v128, s83, v140
	ds_read_b128 v[160:163], v128
	ds_read_b128 v[164:167], v128 offset:1024
	ds_read_b128 v[168:171], v128 offset:2048
	ds_read_b128 v[172:175], v128 offset:3072
	s_add_u32 s80, s40, 0x40000
	v_mov_b32_e32 v128, v136
	s_mov_b32 m0, s48
	ds_read_b128 v[176:179], v143 offset:32768
	ds_read_b128 v[180:183], v143 offset:33792
	ds_read_b128 v[184:187], v143 offset:34816
	ds_read_b128 v[188:191], v143 offset:35840
	ds_read_b128 v[192:195], v143 offset:36864
	ds_read_b128 v[196:199], v143 offset:37888
	ds_read_b128 v[200:203], v143 offset:38912
	ds_read_b128 v[204:207], v143 offset:39936
	s_addc_u32 s81, s41, 0
	s_nop 0
	global_load_lds_dwordx4 v128, s[80:81]
	v_mov_b32_e32 v128, v138
	s_mov_b32 m0, s49
	s_nop 0
	global_load_lds_dwordx4 v128, s[80:81]
	s_waitcnt vmcnt(8)
	s_waitcnt lgkmcnt(0)
	s_barrier
	s_waitcnt lgkmcnt(0)
	v_mfma_i32_16x16x64_i8 v[124:127], v[144:147], v[176:179], v[124:127]
	v_mfma_i32_16x16x64_i8 v[120:123], v[152:155], v[176:179], v[120:123]
	v_mfma_i32_16x16x64_i8 v[108:111], v[144:147], v[184:187], v[108:111]
	v_mfma_i32_16x16x64_i8 v[104:107], v[152:155], v[184:187], v[104:107]
	v_mfma_i32_16x16x64_i8 v[92:95], v[144:147], v[192:195], v[92:95]
	v_mfma_i32_16x16x64_i8 v[88:91], v[152:155], v[192:195], v[88:91]
	v_mfma_i32_16x16x64_i8 v[76:79], v[144:147], v[200:203], v[76:79]
	v_mfma_i32_16x16x64_i8 v[72:75], v[152:155], v[200:203], v[72:75]
	v_mfma_i32_16x16x64_i8 v[124:127], v[148:151], v[180:183], v[124:127]
	v_mfma_i32_16x16x64_i8 v[120:123], v[156:159], v[180:183], v[120:123]
	v_mfma_i32_16x16x64_i8 v[108:111], v[148:151], v[188:191], v[108:111]
	v_mfma_i32_16x16x64_i8 v[104:107], v[156:159], v[188:191], v[104:107]
	v_mfma_i32_16x16x64_i8 v[92:95], v[148:151], v[196:199], v[92:95]
	v_mfma_i32_16x16x64_i8 v[88:91], v[156:159], v[196:199], v[88:91]
	v_mfma_i32_16x16x64_i8 v[76:79], v[148:151], v[204:207], v[76:79]
	v_mfma_i32_16x16x64_i8 v[72:75], v[156:159], v[204:207], v[72:75]
	v_mfma_i32_16x16x64_i8 v[116:119], v[160:163], v[176:179], v[116:119]
	v_mfma_i32_16x16x64_i8 v[112:115], v[168:171], v[176:179], v[112:115]
	v_mfma_i32_16x16x64_i8 v[100:103], v[160:163], v[184:187], v[100:103]
	v_mfma_i32_16x16x64_i8 v[96:99], v[168:171], v[184:187], v[96:99]
	v_mfma_i32_16x16x64_i8 v[84:87], v[160:163], v[192:195], v[84:87]
	v_mfma_i32_16x16x64_i8 v[80:83], v[168:171], v[192:195], v[80:83]
	v_mfma_i32_16x16x64_i8 v[68:71], v[160:163], v[200:203], v[68:71]
	v_mfma_i32_16x16x64_i8 v[64:67], v[168:171], v[200:203], v[64:67]
	v_mfma_i32_16x16x64_i8 v[116:119], v[164:167], v[180:183], v[116:119]
	v_mfma_i32_16x16x64_i8 v[112:115], v[172:175], v[180:183], v[112:115]
	v_mfma_i32_16x16x64_i8 v[100:103], v[164:167], v[188:191], v[100:103]
	v_mfma_i32_16x16x64_i8 v[96:99], v[172:175], v[188:191], v[96:99]
	v_mfma_i32_16x16x64_i8 v[84:87], v[164:167], v[196:199], v[84:87]
	v_mfma_i32_16x16x64_i8 v[80:83], v[172:175], v[196:199], v[80:83]
	v_mfma_i32_16x16x64_i8 v[68:71], v[164:167], v[204:207], v[68:71]
	v_mfma_i32_16x16x64_i8 v[64:67], v[172:175], v[204:207], v[64:67]
	s_barrier
; #define PG8_STAGE(bufoff, gbase, voff) do { _Pragma("unroll") for (int _i = 0; _i < 2; ++_i) { unsigned _vo = (voff)[_i]; asm volatile("" : "+v"(_vo));   \
;         __builtin_amdgcn_global_load_lds((const unsigned*)((const char*)(gbase) + _vo), (LAS unsigned*)(lds + (bufoff) + ldsw + _i * 8192), 16, 0, 0); } } while (0)
; #define PG8_LDA(dst, b, h) do { _Pragma("unroll") for (int m = 0; m < 4; ++m) _Pragma("unroll") for (int k = 0; k < 2; ++k) dst[m][k] = *(const LAS bf16x8*)(lds + PG8_SA(b, h) + aoff + m * 2048 + k * 1024); } while (0)
; #define PG8_WAIT_V(n) asm volatile("s_waitcnt vmcnt(" #n ")" ::: "memory")
; #define PG8_WAIT_L(n) asm volatile("s_waitcnt lgkmcnt(" #n ")" ::: "memory")
; #define PG8_BAR __builtin_amdgcn_s_barrier()
; #define PG8_SCHED __builtin_amdgcn_sched_barrier(0)
; template <bool F8 = false>
; __device__ __forceinline__ void gemm_phase(LAS unsigned char* lds, const int K, const Sched& S, const Epi& E, const int wave_s) {
;     ...
;             PG8_LDA(At, 1, 1); PG8_STAGE(PG8_SB(1, 0), b3, voffB); PG8_STAGE(PG8_SB(1, 1), b3 + hstepB, voffB); PG8_STAGE(PG8_SA(1, 0), a3, voffA);
;             PG8_WAIT_V(8); PG8_WAIT_L(0); PG8_BAR; PG8_MMA(1, 0, At, B0); PG8_MMA(1, 1, At, B1); PG8_BAR; PG8_SCHED;
;         }
;         if (align) { if (wr == 0) PG8_BAR; }
	v_mov_b32_e32 v128, v137
	ds_read_b128 v[176:179], v143 offset:49152
	ds_read_b128 v[180:183], v143 offset:50176
	ds_read_b128 v[184:187], v143 offset:51200
	ds_read_b128 v[188:191], v143 offset:52224
	ds_read_b128 v[192:195], v143 offset:53248
	ds_read_b128 v[196:199], v143 offset:54272
	ds_read_b128 v[200:203], v143 offset:55296
	ds_read_b128 v[204:207], v143 offset:56320
	s_add_i32 s80, s82, s73
	v_lshl_add_u64 v[134:135], s[42:43], 0, v[128:129]
	v_lshl_add_u64 v[134:135], v[134:135], 0, s[14:15]
	s_mov_b32 m0, s80
	v_mov_b32_e32 v128, v139
	global_load_lds_dwordx4 v[134:135], off
	s_add_i32 m0, s80, 0x2000
	s_nop 0
	v_lshl_add_u64 v[134:135], s[42:43], 0, v[128:129]
	s_add_u32 s42, s42, 0x40080
	v_lshl_add_u64 v[134:135], v[134:135], 0, s[14:15]
	s_addc_u32 s43, s43, 0
	v_mov_b32_e32 v128, v137
	s_add_i32 s80, s83, s73
	global_load_lds_dwordx4 v[134:135], off
	s_mov_b32 m0, s80
	s_nop 0
	global_load_lds_dwordx4 v128, s[42:43]
	v_mov_b32_e32 v128, v139
	s_add_i32 m0, s80, 0x2000
	s_nop 0
	global_load_lds_dwordx4 v128, s[42:43]
	v_mov_b32_e32 v128, v136
	s_mov_b32 m0, s55
	v_lshl_add_u64 v[134:135], s[40:41], 0, v[128:129]
	v_lshl_add_u64 v[134:135], v[134:135], 0, s[14:15]
	v_mov_b32_e32 v128, v138
	global_load_lds_dwordx4 v[134:135], off
	s_mov_b32 m0, s61
	v_lshl_add_u64 v[134:135], s[40:41], 0, v[128:129]
	v_lshl_add_u64 v[134:135], v[134:135], 0, s[14:15]
	global_load_lds_dwordx4 v[134:135], off
	s_waitcnt vmcnt(8)
	s_waitcnt lgkmcnt(0)
	s_barrier
	s_waitcnt lgkmcnt(0)
	v_mfma_i32_16x16x64_i8 v[60:63], v[144:147], v[176:179], v[60:63]
	v_mfma_i32_16x16x64_i8 v[56:59], v[152:155], v[176:179], v[56:59]
	v_mfma_i32_16x16x64_i8 v[44:47], v[144:147], v[184:187], v[44:47]
	v_mfma_i32_16x16x64_i8 v[40:43], v[152:155], v[184:187], v[40:43]
	v_mfma_i32_16x16x64_i8 v[28:31], v[144:147], v[192:195], v[28:31]
	v_mfma_i32_16x16x64_i8 v[24:27], v[152:155], v[192:195], v[24:27]
	v_mfma_i32_16x16x64_i8 v[12:15], v[144:147], v[200:203], v[12:15]
	v_mfma_i32_16x16x64_i8 v[8:11], v[152:155], v[200:203], v[8:11]
	v_mfma_i32_16x16x64_i8 v[60:63], v[148:151], v[180:183], v[60:63]
	v_mfma_i32_16x16x64_i8 v[56:59], v[156:159], v[180:183], v[56:59]
	v_mfma_i32_16x16x64_i8 v[44:47], v[148:151], v[188:191], v[44:47]
	v_mfma_i32_16x16x64_i8 v[40:43], v[156:159], v[188:191], v[40:43]
	v_mfma_i32_16x16x64_i8 v[28:31], v[148:151], v[196:199], v[28:31]
	v_mfma_i32_16x16x64_i8 v[24:27], v[156:159], v[196:199], v[24:27]
	v_mfma_i32_16x16x64_i8 v[12:15], v[148:151], v[204:207], v[12:15]
	v_mfma_i32_16x16x64_i8 v[8:11], v[156:159], v[204:207], v[8:11]
	v_mfma_i32_16x16x64_i8 v[52:55], v[160:163], v[176:179], v[52:55]
	v_mfma_i32_16x16x64_i8 v[48:51], v[168:171], v[176:179], v[48:51]
	v_mfma_i32_16x16x64_i8 v[36:39], v[160:163], v[184:187], v[36:39]
	v_mfma_i32_16x16x64_i8 v[32:35], v[168:171], v[184:187], v[32:35]
	v_mfma_i32_16x16x64_i8 v[20:23], v[160:163], v[192:195], v[20:23]
	v_mfma_i32_16x16x64_i8 v[16:19], v[168:171], v[192:195], v[16:19]
	v_mfma_i32_16x16x64_i8 v[4:7], v[160:163], v[200:203], v[4:7]
	v_mfma_i32_16x16x64_i8 v[0:3], v[168:171], v[200:203], v[0:3]
	v_mfma_i32_16x16x64_i8 v[52:55], v[164:167], v[180:183], v[52:55]
	v_mfma_i32_16x16x64_i8 v[48:51], v[172:175], v[180:183], v[48:51]
	v_mfma_i32_16x16x64_i8 v[36:39], v[164:167], v[188:191], v[36:39]
	v_mfma_i32_16x16x64_i8 v[32:35], v[172:175], v[188:191], v[32:35]
	v_mfma_i32_16x16x64_i8 v[20:23], v[164:167], v[196:199], v[20:23]
	v_mfma_i32_16x16x64_i8 v[16:19], v[172:175], v[196:199], v[16:19]
	v_mfma_i32_16x16x64_i8 v[4:7], v[164:167], v[204:207], v[4:7]
	v_mfma_i32_16x16x64_i8 v[0:3], v[172:175], v[204:207], v[0:3]
	s_barrier
	s_add_i32 s63, s63, 2
	s_add_u32 s38, s38, 0x100
	s_addc_u32 s39, s39, 0
	s_add_u32 s25, s25, 0x100
	s_addc_u32 s62, s62, 0
	s_cmp_gt_u32 s63, 13
	s_cbranch_scc0 .LBB0_1860
	s_setprio 0
	s_and_b64 vcc, exec, s[16:17]
	s_cbranch_vccz .LBB0_1863
	s_barrier
